# MFMA-shadow fill: accumulator-zeroing MFMAs moved to the top of each GEMM tile-loop head (scheduler VALU temp renamed out of the accumulator range) so they run under the tile scheduler's scalar work
# speedup vs baseline: 1.0027x; 1.0027x over previous
;     __device__ __forceinline__ const char* pa(const Unit& u) const { return (const char*)(A + (size_t)u.pm * a_tile_stride + (size_t)((u.pn >> a_group_shift) * a_group_cols)); }
;     __device__ __forceinline__ const char* pb(const Unit& u) const { return (const char*)(Bt + (size_t)u.pn * b_tile_stride); }
;     __device__ __forceinline__ const char* pa(const Unit& u) const { return (const char*)(A + (size_t)u.pm * a_tile_stride + (size_t)u.pn * 512); }
; template <class PT, class Epi>
; __device__ __forceinline__ void gemm_phase_once(LAS unsigned char* lds, const PT& S, const Epi& E, bool epi_on) {
;     ...
;         const bool has_next = S.next(ui + 1, nxt);
;         const char* nA = has_next ? S.pa(nxt) : cA; const char* nB = has_next ? S.pb(nxt) : cB;
.LBB0_324:
	s_add_i32 s31, s31, 1
	s_cmp_ge_u32 s31, s0
	s_mov_b64 s[24:25], 0
	v_mov_b32_e32 v2, 0
	v_mov_b32_e32 v3, 0
	v_mov_b32_e32 v4, 0
	v_mov_b32_e32 v5, 0
	s_nop 1
	v_mfma_f32_16x16x32_bf16 v[6:9], v[2:5], v[2:5], 0
	v_mfma_f32_16x16x32_bf16 v[10:13], v[2:5], v[2:5], 0
	v_mfma_f32_16x16x32_bf16 v[14:17], v[2:5], v[2:5], 0
	v_mfma_f32_32x32x16_bf16 v[18:33], v[2:5], v[2:5], 0
	v_mfma_f32_32x32x16_bf16 v[34:49], v[2:5], v[2:5], 0
	v_mfma_f32_32x32x16_bf16 v[50:65], v[2:5], v[2:5], 0
	v_mfma_f32_32x32x16_bf16 v[66:81], v[2:5], v[2:5], 0
	v_mfma_f32_32x32x16_bf16 v[82:97], v[2:5], v[2:5], 0
	v_mfma_f32_32x32x16_bf16 v[98:113], v[2:5], v[2:5], 0
	v_mfma_f32_32x32x16_bf16 v[114:129], v[2:5], v[2:5], 0
	s_cbranch_scc1 .LBB0_327
	s_lshl_b32 s7, s31, 7
	s_add_i32 s7, s36, s7
	s_cmpk_gt_i32 s7, 0xa3f
	s_cbranch_scc1 .LBB0_327
	s_ashr_i32 s6, s7, 31
	s_lshr_b32 s6, s6, 29
	s_add_i32 s6, s7, s6
	s_ashr_i32 s10, s6, 3
	s_and_b32 s6, s6, -8
	s_sub_i32 s6, s7, s6
	s_cmp_lt_i32 s6, 0
	s_cselect_b32 s7, s27, 0x148
	s_mul_i32 s6, s7, s6
	s_add_i32 s6, s6, s10
	s_mul_hi_i32 s7, s6, 0x63e7063f
	s_lshr_b32 s10, s7, 31
	s_ashr_i32 s7, s7, 7
	s_add_i32 s7, s7, s10
	s_lshl_b32 s10, s7, 3
	s_mulk_i32 s7, 0x148
	s_sub_i32 s6, s6, s7
	s_bfe_u32 s7, s6, 0x3001c
	s_add_i32 s7, s6, s7
	s_sext_i32_i16 s11, s7
	s_and_b32 s7, s7, 0xfff8
	s_sub_i32 s6, s6, s7
	s_sext_i32_i16 s6, s6
	s_add_i32 s6, s10, s6
	s_ashr_i32 s10, s11, 3
	s_mov_b64 s[24:25], -1
.LBB0_327:
	s_ashr_i32 s7, s6, 31
	s_xor_b64 s[14:15], s[24:25], -1
	s_lshl_b64 s[12:13], s[6:7], 20
	s_add_u32 s12, s72, s12
	s_addc_u32 s13, s73, s13
	s_and_b64 s[16:17], s[24:25], exec
	s_cselect_b32 s7, s13, s21
	s_cselect_b32 s41, s12, s20
	s_ashr_i32 s11, s10, 31
	s_lshl_b64 s[16:17], s[10:11], 20
	v_readlane_b32 s42, v254, 5
	v_readlane_b32 s43, v254, 6
	s_add_u32 s16, s42, s16
	s_addc_u32 s17, s43, s17
	s_and_b64 s[24:25], s[24:25], exec
	s_cselect_b32 s11, s17, s23
	s_cselect_b32 s42, s16, s22
	s_add_u32 s20, s20, 0x80080
	s_addc_u32 s21, s21, 0
	s_add_u32 s43, s22, 0x100
	s_addc_u32 s44, s23, 0
	s_mov_b32 s45, -2

;     __device__ __forceinline__ bool next(int i, Unit& u) const {
;         const int nwg = nM * nN; const long L = (long)i * G + c; if (L >= nwg) return false;
;         int wgid = (int)L; { const int q = nwg / NXCD, r = nwg % NXCD, xcd = wgid % NXCD, off = wgid / NXCD; wgid = (xcd < r ? xcd * (q + 1) : r * (q + 1) + (xcd - r) * q) + off; }
;         const int nig = WGM * nN, gid = wgid / nig, fm = gid * WGM, gsz = (nM - fm) < WGM ? (nM - fm) : WGM;
.LBB0_614:
	s_add_i32 s27, s27, 1
	s_mul_i32 s2, s27, s30
	s_mul_hi_u32 s3, s27, s33
	v_mov_b32_e32 v2, 0
	v_mov_b32_e32 v3, 0
	v_mov_b32_e32 v4, 0
	v_mov_b32_e32 v5, 0
	s_nop 1
	v_mfma_f32_16x16x32_bf16 v[6:9], v[2:5], v[2:5], 0
	v_mfma_f32_16x16x32_bf16 v[10:13], v[2:5], v[2:5], 0
	v_mfma_f32_16x16x32_bf16 v[14:17], v[2:5], v[2:5], 0
	v_mfma_f32_32x32x16_bf16 v[18:33], v[2:5], v[2:5], 0
	v_mfma_f32_32x32x16_bf16 v[34:49], v[2:5], v[2:5], 0
	v_mfma_f32_32x32x16_bf16 v[50:65], v[2:5], v[2:5], 0
	v_mfma_f32_32x32x16_bf16 v[66:81], v[2:5], v[2:5], 0
	v_mfma_f32_32x32x16_bf16 v[82:97], v[2:5], v[2:5], 0
	v_mfma_f32_32x32x16_bf16 v[98:113], v[2:5], v[2:5], 0
	v_mfma_f32_32x32x16_bf16 v[114:129], v[2:5], v[2:5], 0
	s_add_i32 s3, s3, s2
	s_mul_i32 s2, s27, s33
	v_readlane_b32 s6, v254, 9
	s_add_u32 s14, s2, s6
	s_addc_u32 s15, s3, s1
	v_cmp_gt_i64_e64 s[2:3], s[14:15], v[144:145]
	v_cmp_lt_i64_e64 s[6:7], s[14:15], v[142:143]
	s_and_b64 vcc, exec, s[2:3]
	s_cbranch_vccnz .LBB0_620
	s_ashr_i32 s12, s14, 31
	s_lshr_b32 s12, s12, 29
	s_add_i32 s15, s14, s12
	s_and_b32 s12, s15, -8
	s_sub_i32 s14, s14, s12
	s_cmp_gt_i32 s14, -1
	s_mov_b64 s[12:13], -1
	s_cbranch_scc0 .LBB0_617
	s_lshl_b32 s16, s14, 6
	s_mov_b64 s[12:13], 0

;     __device__ __forceinline__ bool next(int i, Unit& u) const {
;     ...
;         const int nig = WGM * nN, gid = wgid / nig, fm = gid * WGM, gsz = (nM - fm) < WGM ? (nM - fm) : WGM;
;         u.pm = fm + ((wgid % nig) % gsz); u.pn = (wgid % nig) / gsz; return true;
.LBB0_619:
	s_ashr_i32 s12, s15, 3
	s_add_i32 s12, s16, s12
	s_ashr_i32 s13, s12, 31
	s_lshr_b32 s13, s13, 26
	s_add_i32 s13, s12, s13
	s_ashr_i32 s14, s13, 6
	s_lshl_b32 s14, s14, 3
	s_sub_i32 s15, 64, s14
	s_min_i32 s15, s15, 8
	s_abs_i32 s16, s15
	v_cvt_f32_u32_e32 v156, s16
	s_sub_i32 s35, 0, s16
	s_andn2_b32 s13, s13, 63
	s_sub_i32 s13, s12, s13
	v_rcp_iflag_f32_e32 v156, v156
	s_abs_i32 s12, s13
	s_xor_b32 s17, s13, s15
	s_ashr_i32 s17, s17, 31
	v_mul_f32_e32 v156, 0x4f7ffffe, v156
	v_cvt_u32_f32_e32 v156, v156
	s_nop 0
	v_readfirstlane_b32 s38, v156
	s_mul_i32 s35, s35, s38
	s_mul_hi_u32 s35, s38, s35
	s_add_i32 s38, s38, s35
	s_mul_hi_u32 s35, s12, s38
	s_mul_i32 s38, s35, s16
	s_sub_i32 s12, s12, s38
	s_add_i32 s39, s35, 1
	s_sub_i32 s38, s12, s16
	s_cmp_ge_u32 s12, s16
	s_cselect_b32 s35, s39, s35
	s_cselect_b32 s12, s38, s12
	s_add_i32 s38, s35, 1
	s_cmp_ge_u32 s12, s16
	s_cselect_b32 s12, s38, s35
	s_xor_b32 s12, s12, s17
	s_sub_i32 s12, s12, s17
	s_mul_i32 s15, s12, s15
	s_sub_i32 s13, s13, s15
	s_add_i32 s35, s14, s13

;     __device__ __forceinline__ const char* pa(const Unit& u) const { return (const char*)(A + (size_t)u.pm * a_tile_stride + (size_t)u.pn * 512); }
;     __device__ __forceinline__ const char* pa(const Unit& u) const { return (const char*)(A + (size_t)u.pm * a_tile_stride + (size_t)((u.pn >> a_group_shift) * a_group_cols)); }
;     __device__ __forceinline__ const char* pb(const Unit& u) const { return (const char*)(Bt + (size_t)u.pn * b_tile_stride); }
; template <class PT, class Epi>
; __device__ __forceinline__ void gemm_phase_once(LAS unsigned char* lds, const PT& S, const Epi& E, bool epi_on) {
;     ...
;         const bool has_next = S.next(ui + 1, nxt);
;         const char* nA = has_next ? S.pa(nxt) : cA; const char* nB = has_next ? S.pb(nxt) : cB;
.LBB0_622:
	s_ashr_i32 s13, s12, 31
	s_lshl_b64 s[16:17], s[12:13], 21
	s_add_u32 s16, s92, s16
	s_addc_u32 s17, s93, s17
	s_and_b64 s[6:7], s[6:7], exec
	s_cselect_b32 s13, s17, s19
	s_cselect_b32 s38, s16, s18
	s_add_u32 s6, s20, 0x180080
	s_addc_u32 s7, s21, 0
	s_add_u32 s39, s18, 0x100
	s_addc_u32 s40, s19, 0
	s_mov_b32 s41, -2

;     __device__ __forceinline__ bool next(int i, Unit& u) const {
;         const int nwg = nM * nN; const long L = (long)i * G + c; if (L >= nwg) return false;
;         int wgid = (int)L; { const int q = nwg / NXCD, r = nwg % NXCD, xcd = wgid % NXCD, off = wgid / NXCD; wgid = (xcd < r ? xcd * (q + 1) : r * (q + 1) + (xcd - r) * q) + off; }
;         const int nig = WGM * nN, gid = wgid / nig, fm = gid * WGM, gsz = (nM - fm) < WGM ? (nM - fm) : WGM;
.LBB0_750:
	s_add_i32 s30, s30, 1
	s_mul_i32 s0, s30, s35
	s_mul_hi_u32 s1, s30, s33
	v_mov_b32_e32 v2, 0
	v_mov_b32_e32 v3, 0
	v_mov_b32_e32 v4, 0
	v_mov_b32_e32 v5, 0
	s_nop 1
	v_mfma_f32_16x16x32_bf16 v[6:9], v[2:5], v[2:5], 0
	v_mfma_f32_16x16x32_bf16 v[10:13], v[2:5], v[2:5], 0
	v_mfma_f32_16x16x32_bf16 v[14:17], v[2:5], v[2:5], 0
	v_mfma_f32_32x32x16_bf16 v[18:33], v[2:5], v[2:5], 0
	v_mfma_f32_32x32x16_bf16 v[34:49], v[2:5], v[2:5], 0
	v_mfma_f32_32x32x16_bf16 v[50:65], v[2:5], v[2:5], 0
	v_mfma_f32_32x32x16_bf16 v[66:81], v[2:5], v[2:5], 0
	v_mfma_f32_32x32x16_bf16 v[82:97], v[2:5], v[2:5], 0
	v_mfma_f32_32x32x16_bf16 v[98:113], v[2:5], v[2:5], 0
	v_mfma_f32_32x32x16_bf16 v[114:129], v[2:5], v[2:5], 0
	s_add_i32 s1, s1, s0
	s_mul_i32 s0, s30, s33
	v_readlane_b32 s9, v254, 9
	s_add_u32 s12, s0, s9
	s_addc_u32 s13, s1, s25
	v_cmp_gt_i64_e64 s[0:1], s[12:13], v[144:145]
	s_and_b64 vcc, exec, s[0:1]
	s_cbranch_vccnz .LBB0_756
	s_ashr_i32 s8, s12, 31
	s_lshr_b32 s8, s8, 29
	s_add_i32 s10, s12, s8
	s_and_b32 s8, s10, -8
	s_sub_i32 s11, s12, s8
	s_cmp_gt_i32 s11, -1
	s_mov_b64 s[8:9], -1
	s_cbranch_scc0 .LBB0_753
	s_lshl_b32 s14, s11, 4
	s_mov_b64 s[8:9], 0

;     __device__ __forceinline__ const char* pa(const Unit& u) const { return (const char*)(A + (size_t)u.pm * a_tile_stride + (size_t)u.pn * 512); }
;     __device__ __forceinline__ bool next(int i, Unit& u) const {
;     ...
;         const int nig = WGM * nN, gid = wgid / nig, fm = gid * WGM, gsz = (nM - fm) < WGM ? (nM - fm) : WGM;
;         u.pm = fm + ((wgid % nig) % gsz); u.pn = (wgid % nig) / gsz; return true;
;     }
;     __device__ __forceinline__ const char* pa(const Unit& u) const { return (const char*)(A + (size_t)u.pm * a_tile_stride + (size_t)((u.pn >> a_group_shift) * a_group_cols)); }
;     __device__ __forceinline__ const char* pb(const Unit& u) const { return (const char*)(Bt + (size_t)u.pn * b_tile_stride); }
.LBB0_755:
	s_ashr_i32 s8, s10, 3
	s_add_i32 s8, s14, s8
	s_ashr_i32 s9, s8, 31
	s_lshr_b32 s9, s9, 28
	s_add_i32 s9, s8, s9
	s_ashr_i32 s10, s9, 4
	s_lshl_b32 s10, s10, 3
	s_sub_i32 s11, 64, s10
	s_min_i32 s11, s11, 8
	s_abs_i32 s14, s11
	v_cvt_f32_u32_e32 v165, s14
	s_sub_i32 s22, 0, s14
	s_and_b32 s9, s9, -16
	s_sub_i32 s9, s8, s9
	v_rcp_iflag_f32_e32 v165, v165
	s_abs_i32 s8, s9
	s_xor_b32 s15, s9, s11
	s_ashr_i32 s15, s15, 31
	v_mul_f32_e32 v165, 0x4f7ffffe, v165
	v_cvt_u32_f32_e32 v165, v165
	s_nop 0
	v_readfirstlane_b32 s23, v165
	s_mul_i32 s22, s22, s23
	s_mul_hi_u32 s22, s23, s22
	s_add_i32 s23, s23, s22
	s_mul_hi_u32 s22, s8, s23
	s_mul_i32 s23, s22, s14
	s_sub_i32 s8, s8, s23
	s_add_i32 s39, s22, 1
	s_sub_i32 s23, s8, s14
	s_cmp_ge_u32 s8, s14
	s_cselect_b32 s22, s39, s22
	s_cselect_b32 s8, s23, s8
	s_add_i32 s23, s22, 1
	s_cmp_ge_u32 s8, s14
	s_cselect_b32 s8, s23, s22
	s_xor_b32 s8, s8, s15
	s_sub_i32 s8, s8, s15
	s_mul_i32 s11, s8, s11
	s_sub_i32 s9, s9, s11
	s_add_i32 s10, s10, s9
.LBB0_756:
	s_ashr_i32 s11, s10, 31
	v_cmp_lt_i64_e32 vcc, s[12:13], v[142:143]
	s_lshl_b64 s[12:13], s[10:11], 20
	s_add_u32 s12, s72, s12
	s_addc_u32 s13, s73, s13
	s_and_b64 s[14:15], vcc, exec
	s_cselect_b32 s11, s13, s19
	s_cselect_b32 s39, s12, s18
	s_ashr_i32 s9, s8, 31
	s_lshl_b64 s[14:15], s[8:9], 20
	s_add_u32 s14, s84, s14
	s_addc_u32 s15, s85, s15
	s_and_b64 s[22:23], vcc, exec
	s_cselect_b32 s9, s15, s21
	s_cselect_b32 s40, s14, s20
	s_add_u32 s18, s18, 0x80080
	s_addc_u32 s19, s19, 0
	s_add_u32 s41, s20, 0x100
	s_addc_u32 s42, s21, 0
	s_mov_b32 s43, -2

;     __device__ __forceinline__ bool next(int i, Unit& u) const {
;         const int nwg = nM * nN; const long L = (long)i * G + c; if (L >= nwg) return false;
;         int wgid = (int)L; { const int q = nwg / NXCD, r = nwg % NXCD, xcd = wgid % NXCD, off = wgid / NXCD; wgid = (xcd < r ? xcd * (q + 1) : r * (q + 1) + (xcd - r) * q) + off; }
;         const int nig = WGM * nN, gid = wgid / nig, fm = gid * WGM, gsz = (nM - fm) < WGM ? (nM - fm) : WGM;
.LBB0_773:
	s_add_i32 s35, s35, 1
	s_mul_i32 s1, s35, s39
	s_mul_hi_u32 s8, s35, s33
	v_mov_b32_e32 v2, 0
	v_mov_b32_e32 v3, 0
	v_mov_b32_e32 v4, 0
	v_mov_b32_e32 v5, 0
	s_nop 1
	v_mfma_f32_16x16x32_bf16 v[6:9], v[2:5], v[2:5], 0
	v_mfma_f32_16x16x32_bf16 v[10:13], v[2:5], v[2:5], 0
	v_mfma_f32_16x16x32_bf16 v[14:17], v[2:5], v[2:5], 0
	v_mfma_f32_32x32x16_bf16 v[18:33], v[2:5], v[2:5], 0
	v_mfma_f32_32x32x16_bf16 v[34:49], v[2:5], v[2:5], 0
	v_mfma_f32_32x32x16_bf16 v[50:65], v[2:5], v[2:5], 0
	v_mfma_f32_32x32x16_bf16 v[66:81], v[2:5], v[2:5], 0
	v_mfma_f32_32x32x16_bf16 v[82:97], v[2:5], v[2:5], 0
	v_mfma_f32_32x32x16_bf16 v[98:113], v[2:5], v[2:5], 0
	v_mfma_f32_32x32x16_bf16 v[114:129], v[2:5], v[2:5], 0
	s_add_i32 s8, s8, s1
	s_mul_i32 s1, s35, s33
	s_add_u32 s14, s1, s26
	s_addc_u32 s15, s8, s40
	v_cmp_gt_i64_e64 s[8:9], s[14:15], 15
	s_and_b64 vcc, exec, s[8:9]
	s_cbranch_vccnz .LBB0_779
	s_ashr_i32 s1, s14, 31
	s_lshr_b32 s1, s1, 29
	s_add_i32 s1, s14, s1
	s_and_b32 s10, s1, -8
	s_sub_i32 s12, s14, s10
	s_cmp_gt_i32 s12, -1
	s_mov_b64 s[10:11], -1
	s_cbranch_scc0 .LBB0_776
	s_lshl_b32 s13, s12, 1
	s_mov_b64 s[10:11], 0

;     __device__ __forceinline__ const char* pa(const Unit& u) const { return (const char*)(A + (size_t)u.pm * a_tile_stride + (size_t)u.pn * 512); }
;     __device__ __forceinline__ bool next(int i, Unit& u) const {
;     ...
;         const int nig = WGM * nN, gid = wgid / nig, fm = gid * WGM, gsz = (nM - fm) < WGM ? (nM - fm) : WGM;
;         u.pm = fm + ((wgid % nig) % gsz); u.pn = (wgid % nig) / gsz; return true;
;     }
;     __device__ __forceinline__ const char* pa(const Unit& u) const { return (const char*)(A + (size_t)u.pm * a_tile_stride + (size_t)((u.pn >> a_group_shift) * a_group_cols)); }
;     __device__ __forceinline__ const char* pb(const Unit& u) const { return (const char*)(Bt + (size_t)u.pn * b_tile_stride); }
.LBB0_778:
	s_ashr_i32 s1, s1, 3
	s_add_i32 s1, s13, s1
	s_ashr_i32 s10, s1, 31
	s_lshr_b32 s10, s10, 27
	s_add_i32 s10, s1, s10
	s_ashr_i32 s11, s10, 5
	s_lshl_b32 s11, s11, 3
	s_sub_i32 s12, 4, s11
	s_min_i32 s12, s12, 8
	s_abs_i32 s13, s12
	v_cvt_f32_u32_e32 v138, s13
	s_sub_i32 s17, 0, s13
	s_andn2_b32 s10, s10, 31
	s_sub_i32 s1, s1, s10
	v_rcp_iflag_f32_e32 v138, v138
	s_abs_i32 s10, s1
	s_xor_b32 s16, s1, s12
	s_ashr_i32 s16, s16, 31
	v_mul_f32_e32 v138, 0x4f7ffffe, v138
	v_cvt_u32_f32_e32 v138, v138
	s_nop 0
	v_readfirstlane_b32 s19, v138
	s_mul_i32 s17, s17, s19
	s_mul_hi_u32 s17, s19, s17
	s_add_i32 s19, s19, s17
	s_mul_hi_u32 s17, s10, s19
	s_mul_i32 s19, s17, s13
	s_sub_i32 s10, s10, s19
	s_add_i32 s24, s17, 1
	s_sub_i32 s19, s10, s13
	s_cmp_ge_u32 s10, s13
	s_cselect_b32 s17, s24, s17
	s_cselect_b32 s10, s19, s10
	s_add_i32 s19, s17, 1
	s_cmp_ge_u32 s10, s13
	s_cselect_b32 s10, s19, s17
	s_xor_b32 s10, s10, s16
	s_sub_i32 s10, s10, s16
	s_mul_i32 s12, s10, s12
	s_sub_i32 s1, s1, s12
	s_add_i32 s12, s11, s1
.LBB0_779:
	s_ashr_i32 s13, s12, 31
	v_cmp_lt_i64_e64 s[24:25], s[14:15], 16
	s_lshl_b64 s[14:15], s[12:13], 20
	s_add_u32 s14, s81, s14
	s_addc_u32 s15, s96, s15
	s_and_b64 s[16:17], s[24:25], exec
	s_cselect_b32 s1, s15, s21
	s_cselect_b32 s13, s14, s20
	s_ashr_i32 s11, s10, 31
	s_lshl_b64 s[16:17], s[10:11], 20
	s_add_u32 s16, s82, s16
	s_addc_u32 s17, s83, s17
	s_and_b64 s[24:25], s[24:25], exec
	s_cselect_b32 s11, s17, s23
	s_cselect_b32 s19, s16, s22
	s_add_u32 s20, s20, 0x80080
	s_addc_u32 s21, s21, 0
	s_add_u32 s45, s22, 0x100
	s_addc_u32 s46, s23, 0
	s_mov_b32 s47, -2

;     __device__ __forceinline__ bool next(int i, Unit& u) const {
;         const int nwg = nM * nN; const long L = (long)i * G + c; if (L >= nwg) return false;
;         int wgid = (int)L; { const int q = nwg / NXCD, r = nwg % NXCD, xcd = wgid % NXCD, off = wgid / NXCD; wgid = (xcd < r ? xcd * (q + 1) : r * (q + 1) + (xcd - r) * q) + off; }
;         const int nig = WGM * nN, gid = wgid / nig, fm = gid * WGM, gsz = (nM - fm) < WGM ? (nM - fm) : WGM;
.LBB0_1119:
	s_add_i32 s30, s30, 1
	s_mul_i32 s0, s30, s35
	s_mul_hi_u32 s1, s30, s33
	v_mov_b32_e32 v4, 0
	v_mov_b32_e32 v5, 0
	v_mov_b32_e32 v6, 0
	v_mov_b32_e32 v7, 0
	s_nop 1
	v_mfma_f32_16x16x32_bf16 v[8:11], v[4:7], v[4:7], 0
	v_mfma_f32_16x16x32_bf16 v[12:15], v[4:7], v[4:7], 0
	v_mfma_f32_16x16x32_bf16 v[16:19], v[4:7], v[4:7], 0
	v_mfma_f32_32x32x16_bf16 v[20:35], v[4:7], v[4:7], 0
	v_mfma_f32_32x32x16_bf16 v[36:51], v[4:7], v[4:7], 0
	v_mfma_f32_32x32x16_bf16 v[52:67], v[4:7], v[4:7], 0
	v_mfma_f32_32x32x16_bf16 v[68:83], v[4:7], v[4:7], 0
	v_mfma_f32_32x32x16_bf16 v[84:99], v[4:7], v[4:7], 0
	v_mfma_f32_32x32x16_bf16 v[100:115], v[4:7], v[4:7], 0
	v_mfma_f32_32x32x16_bf16 v[116:131], v[4:7], v[4:7], 0
	s_add_i32 s1, s1, s0
	s_mul_i32 s0, s30, s33
	v_readlane_b32 s9, v254, 9
	s_add_u32 s14, s0, s9
	s_addc_u32 s15, s1, s25
	v_cmp_gt_i64_e64 s[0:1], s[14:15], v[146:147]
	s_and_b64 vcc, exec, s[0:1]
	s_cbranch_vccnz .LBB0_1125
	s_ashr_i32 s8, s14, 31
	s_lshr_b32 s8, s8, 29
	s_add_i32 s12, s14, s8
	s_and_b32 s8, s12, -8
	s_sub_i32 s13, s14, s8
	s_cmp_gt_i32 s13, -1
	s_mov_b64 s[8:9], -1
	s_cbranch_scc0 .LBB0_1122
	s_lshl_b32 s16, s13, 6
	s_mov_b64 s[8:9], 0

;     __device__ __forceinline__ const char* pa(const Unit& u) const { return (const char*)(A + (size_t)u.pm * a_tile_stride + (size_t)u.pn * 512); }
;     __device__ __forceinline__ bool next(int i, Unit& u) const {
;     ...
;         const int nig = WGM * nN, gid = wgid / nig, fm = gid * WGM, gsz = (nM - fm) < WGM ? (nM - fm) : WGM;
;         u.pm = fm + ((wgid % nig) % gsz); u.pn = (wgid % nig) / gsz; return true;
;     }
;     __device__ __forceinline__ const char* pa(const Unit& u) const { return (const char*)(A + (size_t)u.pm * a_tile_stride + (size_t)((u.pn >> a_group_shift) * a_group_cols)); }
;     __device__ __forceinline__ const char* pb(const Unit& u) const { return (const char*)(Bt + (size_t)u.pn * b_tile_stride); }
.LBB0_1124:
	s_ashr_i32 s8, s12, 3
	s_add_i32 s8, s16, s8
	s_ashr_i32 s9, s8, 31
	s_lshr_b32 s9, s9, 26
	s_add_i32 s9, s8, s9
	s_ashr_i32 s12, s9, 6
	s_lshl_b32 s12, s12, 3
	s_sub_i32 s13, 64, s12
	s_min_i32 s13, s13, 8
	s_abs_i32 s16, s13
	v_cvt_f32_u32_e32 v153, s16
	s_sub_i32 s22, 0, s16
	s_andn2_b32 s9, s9, 63
	s_sub_i32 s9, s8, s9
	v_rcp_iflag_f32_e32 v153, v153
	s_abs_i32 s8, s9
	s_xor_b32 s17, s9, s13
	s_ashr_i32 s17, s17, 31
	v_mul_f32_e32 v153, 0x4f7ffffe, v153
	v_cvt_u32_f32_e32 v153, v153
	s_nop 0
	v_readfirstlane_b32 s23, v153
	s_mul_i32 s22, s22, s23
	s_mul_hi_u32 s22, s23, s22
	s_add_i32 s23, s23, s22
	s_mul_hi_u32 s22, s8, s23
	s_mul_i32 s23, s22, s16
	s_sub_i32 s8, s8, s23
	s_add_i32 s39, s22, 1
	s_sub_i32 s23, s8, s16
	s_cmp_ge_u32 s8, s16
	s_cselect_b32 s22, s39, s22
	s_cselect_b32 s8, s23, s8
	s_add_i32 s23, s22, 1
	s_cmp_ge_u32 s8, s16
	s_cselect_b32 s8, s23, s22
	s_xor_b32 s8, s8, s17
	s_sub_i32 s8, s8, s17
	s_mul_i32 s13, s8, s13
	s_sub_i32 s9, s9, s13
	s_add_i32 s12, s12, s9
.LBB0_1125:
	s_ashr_i32 s13, s12, 31
	v_cmp_lt_i64_e32 vcc, s[14:15], v[144:145]
	s_lshl_b64 s[14:15], s[12:13], 18
	v_readlane_b32 s16, v254, 48
	v_readlane_b32 s17, v254, 49
	s_add_u32 s14, s16, s14
	s_addc_u32 s15, s17, s15
	s_and_b64 s[16:17], vcc, exec
	s_cselect_b32 s13, s15, s19
	s_cselect_b32 s39, s14, s18
	s_ashr_i32 s9, s8, 31
	s_lshl_b64 s[16:17], s[8:9], 18
	v_readlane_b32 s22, v254, 7
	v_readlane_b32 s23, v254, 8
	s_add_u32 s16, s22, s16
	s_addc_u32 s17, s23, s17
	s_and_b64 s[22:23], vcc, exec
	s_cselect_b32 s9, s17, s21
	s_cselect_b32 s40, s16, s20
	s_add_u32 s18, s18, 0x20080
	s_addc_u32 s19, s19, 0
	s_add_u32 s41, s20, 0x100
	s_addc_u32 s42, s21, 0
	s_mov_b32 s43, -2

;     __device__ __forceinline__ const char* pa(const Unit& u) const { return (const char*)(A + (size_t)u.pm * a_tile_stride + (size_t)u.pn * 512); }
;     __device__ __forceinline__ bool next(int i, Unit& u) const {
;         const int nwg = nM * nN; const long L = (long)i * G + c; if (L >= nwg) return false;
;         int wgid = (int)L; { const int q = nwg / NXCD, r = nwg % NXCD, xcd = wgid % NXCD, off = wgid / NXCD; wgid = (xcd < r ? xcd * (q + 1) : r * (q + 1) + (xcd - r) * q) + off; }
;         const int nig = WGM * nN, gid = wgid / nig, fm = gid * WGM, gsz = (nM - fm) < WGM ? (nM - fm) : WGM;
;         u.pm = fm + ((wgid % nig) % gsz); u.pn = (wgid % nig) / gsz; return true;
;     }
;     __device__ __forceinline__ const char* pa(const Unit& u) const { return (const char*)(A + (size_t)u.pm * a_tile_stride + (size_t)((u.pn >> a_group_shift) * a_group_cols)); }
;     __device__ __forceinline__ const char* pb(const Unit& u) const { return (const char*)(Bt + (size_t)u.pn * b_tile_stride); }
.LBB0_1250:
	s_add_i32 s49, s49, 1
	s_mul_i32 s0, s49, s52
	s_mul_hi_u32 s1, s49, s33
	v_mov_b32_e32 v4, 0
	v_mov_b32_e32 v5, 0
	v_mov_b32_e32 v6, 0
	v_mov_b32_e32 v7, 0
	s_nop 1
	v_mfma_f32_16x16x32_bf16 v[8:11], v[4:7], v[4:7], 0
	v_mfma_f32_16x16x32_bf16 v[12:15], v[4:7], v[4:7], 0
	v_mfma_f32_16x16x32_bf16 v[16:19], v[4:7], v[4:7], 0
	v_mfma_f32_32x32x16_bf16 v[20:35], v[4:7], v[4:7], 0
	v_mfma_f32_32x32x16_bf16 v[44:59], v[4:7], v[4:7], 0
	v_mfma_f32_32x32x16_bf16 v[60:75], v[4:7], v[4:7], 0
	v_mfma_f32_32x32x16_bf16 v[76:91], v[4:7], v[4:7], 0
	v_mfma_f32_32x32x16_bf16 v[92:107], v[4:7], v[4:7], 0
	v_mfma_f32_32x32x16_bf16 v[108:123], v[4:7], v[4:7], 0
	v_mfma_f32_32x32x16_bf16 v[124:139], v[4:7], v[4:7], 0
	s_add_i32 s1, s1, s0
	s_mul_i32 s0, s49, s33
	v_readlane_b32 s21, v254, 9
	s_add_u32 s24, s0, s21
	s_addc_u32 s25, s1, s43
	v_cmp_gt_i64_e64 s[0:1], s[24:25], v[156:157]
	s_and_b64 vcc, exec, s[0:1]
	s_cbranch_vccnz .LBB0_1252
	s_ashr_i32 s20, s24, 31
	s_lshr_b32 s20, s20, 29
	s_add_i32 s20, s24, s20
	s_ashr_i32 s21, s20, 3
	s_and_b32 s20, s20, -8
	s_sub_i32 s20, s24, s20
	s_cmp_lt_i32 s20, 0
	s_cselect_b32 s22, s44, 0x160
	s_mul_i32 s20, s22, s20
	s_add_i32 s20, s20, s21
	s_mul_hi_i32 s21, s20, 0x2e8ba2e9
	s_lshr_b32 s22, s21, 31
	s_ashr_i32 s21, s21, 6
	s_add_i32 s21, s21, s22
	s_lshl_b32 s22, s21, 3
	s_sub_i32 s23, 64, s22
	s_min_i32 s23, s23, 8
	s_abs_i32 s26, s23
	v_cvt_f32_u32_e32 v40, s26
	s_sub_i32 s29, 0, s26
	s_mulk_i32 s21, 0x160
	s_sub_i32 s21, s20, s21
	v_rcp_iflag_f32_e32 v40, v40
	s_abs_i32 s20, s21
	s_xor_b32 s27, s21, s23
	s_ashr_i32 s27, s27, 31
	v_mul_f32_e32 v40, 0x4f7ffffe, v40
	v_cvt_u32_f32_e32 v40, v40
	s_nop 0
	v_readfirstlane_b32 s36, v40
	s_mul_i32 s29, s29, s36
	s_mul_hi_u32 s29, s36, s29
	s_add_i32 s36, s36, s29
	s_mul_hi_u32 s29, s20, s36
	s_mul_i32 s36, s29, s26
	s_sub_i32 s20, s20, s36
	s_add_i32 s37, s29, 1
	s_sub_i32 s36, s20, s26
	s_cmp_ge_u32 s20, s26
	s_cselect_b32 s29, s37, s29
	s_cselect_b32 s20, s36, s20
	s_add_i32 s36, s29, 1
	s_cmp_ge_u32 s20, s26
	s_cselect_b32 s20, s36, s29
	s_xor_b32 s20, s20, s27
	s_sub_i32 s20, s20, s27
	s_mul_i32 s23, s20, s23
	s_sub_i32 s21, s21, s23
	s_add_i32 s22, s21, s22
.LBB0_1252:
	s_ashr_i32 s23, s22, 31
	v_cmp_lt_i64_e32 vcc, s[24:25], v[154:155]
	s_lshl_b64 s[24:25], s[22:23], 20
	s_add_u32 s24, s72, s24
	s_addc_u32 s25, s73, s25
	s_and_b64 s[26:27], vcc, exec
	s_cselect_b32 s23, s25, s31
	s_cselect_b32 s29, s24, s30
	s_ashr_i32 s21, s20, 31
	s_lshl_b64 s[26:27], s[20:21], 20
	s_add_u32 s26, s76, s26
	s_addc_u32 s27, s77, s27
	s_and_b64 s[36:37], vcc, exec
	s_cselect_b32 s21, s27, s35
	s_cselect_b32 s58, s26, s34
	s_add_u32 s59, s34, 0x100
	s_addc_u32 s60, s35, 0
	s_mov_b32 s61, -2
	s_waitcnt lgkmcnt(0)
	s_waitcnt vmcnt(0)

;     __device__ __forceinline__ bool next(int i, Unit& u) const {
;         const int nwg = nM * nN; const long L = (long)i * G + c; if (L >= nwg) return false;
;         int wgid = (int)L; { const int q = nwg / NXCD, r = nwg % NXCD, xcd = wgid % NXCD, off = wgid / NXCD; wgid = (xcd < r ? xcd * (q + 1) : r * (q + 1) + (xcd - r) * q) + off; }
;         const int nig = WGM * nN, gid = wgid / nig, fm = gid * WGM, gsz = (nM - fm) < WGM ? (nM - fm) : WGM;
.LBB0_1401:
	s_add_i32 s25, s25, 1
	s_mul_i32 s0, s25, s28
	s_mul_hi_u32 s1, s25, s33
	v_mov_b32_e32 v4, 0
	v_mov_b32_e32 v5, 0
	v_mov_b32_e32 v6, 0
	v_mov_b32_e32 v7, 0
	s_nop 1
	v_mfma_f32_16x16x32_bf16 v[8:11], v[4:7], v[4:7], 0
	v_mfma_f32_16x16x32_bf16 v[12:15], v[4:7], v[4:7], 0
	v_mfma_f32_16x16x32_bf16 v[16:19], v[4:7], v[4:7], 0
	v_mfma_f32_32x32x16_bf16 v[20:35], v[4:7], v[4:7], 0
	v_mfma_f32_32x32x16_bf16 v[36:51], v[4:7], v[4:7], 0
	v_mfma_f32_32x32x16_bf16 v[52:67], v[4:7], v[4:7], 0
	v_mfma_f32_32x32x16_bf16 v[68:83], v[4:7], v[4:7], 0
	v_mfma_f32_32x32x16_bf16 v[84:99], v[4:7], v[4:7], 0
	v_mfma_f32_32x32x16_bf16 v[100:115], v[4:7], v[4:7], 0
	v_mfma_f32_32x32x16_bf16 v[116:131], v[4:7], v[4:7], 0
	s_add_i32 s1, s1, s0
	s_mul_i32 s0, s25, s33
	v_readlane_b32 s2, v254, 9
	s_add_u32 s6, s0, s2
	s_addc_u32 s7, s1, s19
	v_cmp_gt_i64_e64 s[0:1], s[6:7], v[146:147]
	v_cmp_lt_i64_e64 s[2:3], s[6:7], v[144:145]
	s_and_b64 vcc, exec, s[0:1]
	s_cbranch_vccnz .LBB0_1407
	s_ashr_i32 s7, s6, 31
	s_lshr_b32 s7, s7, 29
	s_add_i32 s16, s6, s7
	s_and_b32 s7, s16, -8
	s_sub_i32 s17, s6, s7
	s_cmp_gt_i32 s17, -1
	s_mov_b64 s[6:7], -1
	s_cbranch_scc0 .LBB0_1404
	s_lshl_b32 s31, s17, 6
	s_mov_b64 s[6:7], 0

;     __device__ __forceinline__ const char* pa(const Unit& u) const { return (const char*)(A + (size_t)u.pm * a_tile_stride + (size_t)((u.pn >> a_group_shift) * a_group_cols)); }
;     __device__ __forceinline__ const char* pb(const Unit& u) const { return (const char*)(Bt + (size_t)u.pn * b_tile_stride); }
;     __device__ __forceinline__ const char* pa(const Unit& u) const { return (const char*)(A + (size_t)u.pm * a_tile_stride + (size_t)u.pn * 512); }
;     __device__ __forceinline__ bool next(int i, Unit& u) const {
;     ...
;         const int nig = WGM * nN, gid = wgid / nig, fm = gid * WGM, gsz = (nM - fm) < WGM ? (nM - fm) : WGM;
;         u.pm = fm + ((wgid % nig) % gsz); u.pn = (wgid % nig) / gsz; return true;
; template <class PT, class Epi>
; __device__ __forceinline__ void gemm_phase_once(LAS unsigned char* lds, const PT& S, const Epi& E, bool epi_on) {
;     ...
;         const bool has_next = S.next(ui + 1, nxt);
;         const char* nA = has_next ? S.pa(nxt) : cA; const char* nB = has_next ? S.pb(nxt) : cB;
.LBB0_1406:
	s_ashr_i32 s6, s16, 3
	s_add_i32 s6, s31, s6
	s_ashr_i32 s7, s6, 31
	s_lshr_b32 s7, s7, 26
	s_add_i32 s7, s6, s7
	s_ashr_i32 s16, s7, 6
	s_lshl_b32 s16, s16, 3
	s_sub_i32 s17, 64, s16
	s_min_i32 s17, s17, 8
	s_abs_i32 s31, s17
	v_cvt_f32_u32_e32 v153, s31
	s_sub_i32 s37, 0, s31
	s_andn2_b32 s7, s7, 63
	s_sub_i32 s6, s6, s7
	v_rcp_iflag_f32_e32 v153, v153
	s_abs_i32 s7, s6
	s_xor_b32 s34, s6, s17
	s_ashr_i32 s34, s34, 31
	v_mul_f32_e32 v153, 0x4f7ffffe, v153
	v_cvt_u32_f32_e32 v153, v153
	s_nop 0
	v_readfirstlane_b32 s38, v153
	s_mul_i32 s37, s37, s38
	s_mul_hi_u32 s37, s38, s37
	s_add_i32 s38, s38, s37
	s_mul_hi_u32 s37, s7, s38
	s_mul_i32 s38, s37, s31
	s_sub_i32 s7, s7, s38
	s_add_i32 s39, s37, 1
	s_sub_i32 s38, s7, s31
	s_cmp_ge_u32 s7, s31
	s_cselect_b32 s37, s39, s37
	s_cselect_b32 s7, s38, s7
	s_add_i32 s38, s37, 1
	s_cmp_ge_u32 s7, s31
	s_cselect_b32 s7, s38, s37
	s_xor_b32 s7, s7, s34
	s_sub_i32 s31, s7, s34
	s_mul_i32 s7, s31, s17
	s_sub_i32 s6, s6, s7
	s_add_i32 s34, s16, s6
.LBB0_1407:
	v_cndmask_b32_e64 v153, 0, 1, s[2:3]
	v_cmp_ne_u32_e64 s[6:7], 1, v153
	s_andn2_b64 vcc, exec, s[2:3]
	s_mov_b64 s[2:3], s[12:13]
	s_cbranch_vccnz .LBB0_1409
	s_mul_i32 s2, s34, 0x2c0000
	s_mul_hi_i32 s3, s34, 0x2c0000
	s_add_u32 s2, s78, s2
	s_addc_u32 s3, s79, s3

;     __device__ __forceinline__ const char* pa(const Unit& u) const { return (const char*)(A + (size_t)u.pm * a_tile_stride + (size_t)((u.pn >> a_group_shift) * a_group_cols)); }
;     __device__ __forceinline__ const char* pb(const Unit& u) const { return (const char*)(Bt + (size_t)u.pn * b_tile_stride); }
;     __device__ __forceinline__ const char* pa(const Unit& u) const { return (const char*)(A + (size_t)u.pm * a_tile_stride + (size_t)u.pn * 512); }
; template <class PT, class Epi>
; __device__ __forceinline__ void gemm_phase_once(LAS unsigned char* lds, const PT& S, const Epi& E, bool epi_on) {
;     ...
;         const bool has_next = S.next(ui + 1, nxt);
;         const char* nA = has_next ? S.pa(nxt) : cA; const char* nB = has_next ? S.pb(nxt) : cB;
;         for (int t = 0; t < nt; t += 2) {
;             const bool last = (t == nt - 2);
;             const char* a1 = cA + (size_t)(t + 1) * kstep;
;             const char* a2 = last ? nA : cA + (size_t)(t + 2) * kstep; const char* b2 = last ? nB : cB + (size_t)(t + 2) * kstep;
;             const char* a3 = a2 + kstep; const char* b3 = b2 + kstep;
.LBB0_1411:
	s_add_u32 s12, s12, 0x160080
	s_addc_u32 s13, s13, 0
	s_add_u32 s37, s14, 0x100
	s_addc_u32 s38, s15, 0
	s_mov_b32 s39, -2
	s_waitcnt lgkmcnt(0)

;     __device__ __forceinline__ const char* pa(const Unit& u) const { return (const char*)(A + (size_t)u.pm * a_tile_stride + (size_t)((u.pn >> a_group_shift) * a_group_cols)); }
;     __device__ __forceinline__ const char* pb(const Unit& u) const { return (const char*)(Bt + (size_t)u.pn * b_tile_stride); }
;     __device__ __forceinline__ const char* pa(const Unit& u) const { return (const char*)(A + (size_t)u.pm * a_tile_stride + (size_t)u.pn * 512); }
; template <class PT, class Epi>
; __device__ __forceinline__ void gemm_phase_once(LAS unsigned char* lds, const PT& S, const Epi& E, bool epi_on) {
;     ...
;         const bool has_next = S.next(ui + 1, nxt);
;         const char* nA = has_next ? S.pa(nxt) : cA; const char* nB = has_next ? S.pb(nxt) : cB;
.LBB0_1731:
	s_add_i32 s52, s52, 1
	s_cmp_ge_u32 s52, s44
	s_mov_b64 s[0:1], 0
	v_mov_b32_e32 v4, 0
	v_mov_b32_e32 v5, 0
	v_mov_b32_e32 v6, 0
	v_mov_b32_e32 v7, 0
	s_nop 1
	v_mfma_f32_16x16x32_bf16 v[8:11], v[4:7], v[4:7], 0
	v_mfma_f32_16x16x32_bf16 v[12:15], v[4:7], v[4:7], 0
	v_mfma_f32_16x16x32_bf16 v[16:19], v[4:7], v[4:7], 0
	v_mfma_f32_32x32x16_bf16 v[20:35], v[4:7], v[4:7], 0
	v_mfma_f32_32x32x16_bf16 v[36:51], v[4:7], v[4:7], 0
	v_mfma_f32_32x32x16_bf16 v[52:67], v[4:7], v[4:7], 0
	v_mfma_f32_32x32x16_bf16 v[68:83], v[4:7], v[4:7], 0
	v_mfma_f32_32x32x16_bf16 v[84:99], v[4:7], v[4:7], 0
	v_mfma_f32_32x32x16_bf16 v[100:115], v[4:7], v[4:7], 0
	v_mfma_f32_32x32x16_bf16 v[116:131], v[4:7], v[4:7], 0
	s_cbranch_scc1 .LBB0_1734
	s_lshl_b32 s3, s52, 7
	s_add_i32 s3, s3, s36
	s_cmpk_gt_i32 s3, 0x53f
	s_cbranch_scc1 .LBB0_1734
	s_ashr_i32 s0, s3, 31
	s_lshr_b32 s0, s0, 29
	s_add_i32 s0, s3, s0
	s_ashr_i32 s1, s0, 3
	s_and_b32 s0, s0, -8
	s_sub_i32 s0, s3, s0
	s_cmp_lt_i32 s0, 0
	s_movk_i32 s3, 0xa9
	s_cselect_b32 s3, s3, 0xa8
	s_mul_i32 s0, s3, s0
	s_add_i32 s0, s0, s1
	s_mul_hi_i32 s1, s0, 0x30c30c31
	s_lshr_b32 s3, s1, 31
	s_ashr_i32 s1, s1, 5
	s_add_i32 s1, s1, s3
	s_lshl_b32 s3, s1, 3
	s_mulk_i32 s1, 0xa8
	s_sub_i32 s0, s0, s1
	s_bfe_u32 s1, s0, 0x3001c
	s_add_i32 s1, s0, s1
	s_sext_i32_i16 s15, s1
	s_and_b32 s1, s1, 0xfff8
	s_sub_i32 s0, s0, s1
	s_sext_i32_i16 s0, s0
	s_add_i32 s14, s3, s0
	s_ashr_i32 s20, s15, 3
	s_mov_b64 s[0:1], -1
.LBB0_1734:
	s_ashr_i32 s15, s14, 31
	s_xor_b64 s[24:25], s[0:1], -1
	s_lshl_b64 s[22:23], s[14:15], 20
	s_add_u32 s22, s72, s22
	s_addc_u32 s23, s73, s23
	s_and_b64 s[26:27], s[0:1], exec
	s_cselect_b32 s3, s23, s31
	s_cselect_b32 s15, s22, s30
	s_ashr_i32 s21, s20, 31
	s_lshl_b64 s[26:27], s[20:21], 20
	v_readlane_b32 s34, v254, 5
	v_readlane_b32 s35, v254, 6
	s_add_u32 s26, s34, s26
	s_addc_u32 s27, s35, s27
	s_and_b64 s[0:1], s[0:1], exec
	s_cselect_b32 s21, s27, s29
	s_cselect_b32 s34, s26, s28
	s_add_u32 s0, s30, 0x80080
	s_addc_u32 s1, s31, 0
	s_add_u32 s35, s28, 0x100
	s_addc_u32 s53, s29, 0
	s_mov_b32 s56, -2
	s_waitcnt lgkmcnt(0)
	s_waitcnt vmcnt(0)

;     __device__ __forceinline__ bool next(int i, Unit& u) const {
;         const int nwg = nM * nN; const long L = (long)i * G + c; if (L >= nwg) return false;
;         int wgid = (int)L; { const int q = nwg / NXCD, r = nwg % NXCD, xcd = wgid % NXCD, off = wgid / NXCD; wgid = (xcd < r ? xcd * (q + 1) : r * (q + 1) + (xcd - r) * q) + off; }
;         const int nig = WGM * nN, gid = wgid / nig, fm = gid * WGM, gsz = (nM - fm) < WGM ? (nM - fm) : WGM;
.LBB0_1946:
	s_add_i32 s38, s38, 1
	s_mul_i32 s0, s38, s42
	s_mul_hi_u32 s1, s38, s33
	v_mov_b32_e32 v4, 0
	v_mov_b32_e32 v5, 0
	v_mov_b32_e32 v6, 0
	v_mov_b32_e32 v7, 0
	s_nop 1
	v_mfma_f32_16x16x32_bf16 v[8:11], v[4:7], v[4:7], 0
	v_mfma_f32_16x16x32_bf16 v[12:15], v[4:7], v[4:7], 0
	v_mfma_f32_16x16x32_bf16 v[16:19], v[4:7], v[4:7], 0
	v_mfma_f32_32x32x16_bf16 v[20:35], v[4:7], v[4:7], 0
	v_mfma_f32_32x32x16_bf16 v[36:51], v[4:7], v[4:7], 0
	v_mfma_f32_32x32x16_bf16 v[52:67], v[4:7], v[4:7], 0
	v_mfma_f32_32x32x16_bf16 v[68:83], v[4:7], v[4:7], 0
	v_mfma_f32_32x32x16_bf16 v[84:99], v[4:7], v[4:7], 0
	v_mfma_f32_32x32x16_bf16 v[100:115], v[4:7], v[4:7], 0
	v_mfma_f32_32x32x16_bf16 v[116:131], v[4:7], v[4:7], 0
	s_add_i32 s1, s1, s0
	s_mul_i32 s0, s38, s33
	v_readlane_b32 s2, v254, 9
	s_add_u32 s0, s0, s2
	s_addc_u32 s1, s1, s31
	v_cmp_gt_i64_e64 s[2:3], s[0:1], v[146:147]
	s_and_b64 vcc, exec, s[2:3]
	s_cbranch_vccnz .LBB0_1952
	s_ashr_i32 s6, s0, 31
	s_lshr_b32 s6, s6, 29
	s_add_i32 s20, s0, s6
	s_and_b32 s6, s20, -8
	s_sub_i32 s21, s0, s6
	s_cmp_gt_i32 s21, -1
	s_mov_b64 s[6:7], -1
	s_cbranch_scc0 .LBB0_1949
	s_lshl_b32 s22, s21, 5
	s_mov_b64 s[6:7], 0

;     __device__ __forceinline__ const char* pa(const Unit& u) const { return (const char*)(A + (size_t)u.pm * a_tile_stride + (size_t)((u.pn >> a_group_shift) * a_group_cols)); }
;     __device__ __forceinline__ const char* pb(const Unit& u) const { return (const char*)(Bt + (size_t)u.pn * b_tile_stride); }
;     __device__ __forceinline__ const char* pa(const Unit& u) const { return (const char*)(A + (size_t)u.pm * a_tile_stride + (size_t)u.pn * 512); }
;     __device__ __forceinline__ bool next(int i, Unit& u) const {
;     ...
;         const int nig = WGM * nN, gid = wgid / nig, fm = gid * WGM, gsz = (nM - fm) < WGM ? (nM - fm) : WGM;
;         u.pm = fm + ((wgid % nig) % gsz); u.pn = (wgid % nig) / gsz; return true;
; template <class PT, class Epi>
; __device__ __forceinline__ void gemm_phase_once(LAS unsigned char* lds, const PT& S, const Epi& E, bool epi_on) {
;     ...
;         const bool has_next = S.next(ui + 1, nxt);
;         const char* nA = has_next ? S.pa(nxt) : cA; const char* nB = has_next ? S.pb(nxt) : cB;
.LBB0_1951:
	s_ashr_i32 s6, s20, 3
	s_add_i32 s6, s22, s6
	s_ashr_i32 s7, s6, 31
	s_lshr_b32 s7, s7, 26
	s_add_i32 s7, s6, s7
	s_ashr_i32 s20, s7, 6
	s_lshl_b32 s21, s20, 3
	s_sub_i32 s20, 32, s21
	s_min_i32 s22, s20, 8
	s_abs_i32 s20, s22
	v_cvt_f32_u32_e32 v158, s20
	s_sub_i32 s24, 0, s20
	s_andn2_b32 s7, s7, 63
	s_sub_i32 s6, s6, s7
	v_rcp_iflag_f32_e32 v158, v158
	s_abs_i32 s7, s6
	s_xor_b32 s23, s6, s22
	s_ashr_i32 s23, s23, 31
	v_mul_f32_e32 v158, 0x4f7ffffe, v158
	v_cvt_u32_f32_e32 v158, v158
	s_nop 0
	v_readfirstlane_b32 s25, v158
	s_mul_i32 s24, s24, s25
	s_mul_hi_u32 s24, s25, s24
	s_add_i32 s25, s25, s24
	s_mul_hi_u32 s24, s7, s25
	s_mul_i32 s25, s24, s20
	s_sub_i32 s7, s7, s25
	s_add_i32 s45, s24, 1
	s_sub_i32 s25, s7, s20
	s_cmp_ge_u32 s7, s20
	s_cselect_b32 s24, s45, s24
	s_cselect_b32 s7, s25, s7
	s_add_i32 s25, s24, 1
	s_cmp_ge_u32 s7, s20
	s_cselect_b32 s7, s25, s24
	s_xor_b32 s7, s7, s23
	s_sub_i32 s20, s7, s23
	s_mul_i32 s7, s20, s22
	s_sub_i32 s6, s6, s7
	s_add_i32 s22, s21, s6
.LBB0_1952:
	v_cndmask_b32_e64 v158, 0, 1, s[2:3]
	v_cmp_lt_i64_e64 s[6:7], s[0:1], v[144:145]
	v_cmp_ne_u32_e64 s[0:1], 1, v158
	s_andn2_b64 vcc, exec, s[2:3]
	s_mov_b64 s[2:3], -1
	s_cbranch_vccnz .LBB0_1954
	s_ashr_i32 s21, s20, 31
	s_lshl_b64 s[24:25], s[20:21], 10
	s_mov_b64 s[2:3], 0

;     __device__ __forceinline__ const char* pa(const Unit& u) const { return (const char*)(A + (size_t)u.pm * a_tile_stride + (size_t)((u.pn >> a_group_shift) * a_group_cols)); }
;     __device__ __forceinline__ const char* pb(const Unit& u) const { return (const char*)(Bt + (size_t)u.pn * b_tile_stride); }
;     __device__ __forceinline__ const char* pa(const Unit& u) const { return (const char*)(A + (size_t)u.pm * a_tile_stride + (size_t)u.pn * 512); }
; template <class PT, class Epi>
; __device__ __forceinline__ void gemm_phase_once(LAS unsigned char* lds, const PT& S, const Epi& E, bool epi_on) {
;     ...
;         const bool has_next = S.next(ui + 1, nxt);
;         const char* nA = has_next ? S.pa(nxt) : cA; const char* nB = has_next ? S.pb(nxt) : cB;
;         for (int t = 0; t < nt; t += 2) {
;             const bool last = (t == nt - 2);
;             const char* a1 = cA + (size_t)(t + 1) * kstep;
;             const char* a2 = last ? nA : cA + (size_t)(t + 2) * kstep; const char* b2 = last ? nB : cB + (size_t)(t + 2) * kstep;
;             const char* a3 = a2 + kstep; const char* b3 = b2 + kstep;
.LBB0_1956:
	s_ashr_i32 s46, s22, 4
	s_ashr_i32 s47, s46, 31
	s_lshl_b64 s[46:47], s[46:47], 21
	v_readlane_b32 s48, v254, 52
	v_readlane_b32 s49, v254, 53
	s_add_u32 s21, s48, s46
	s_addc_u32 s23, s49, s47
	s_add_u32 s24, s21, s24
	s_addc_u32 s25, s23, s25
	s_and_b64 s[6:7], s[6:7], exec
	s_cselect_b32 s21, s25, s27
	s_cselect_b32 s23, s24, s26
	s_add_u32 s6, s28, 0x80080
	s_addc_u32 s7, s29, 0
	s_add_u32 s45, s26, 0x100
	s_addc_u32 s46, s27, 0
	s_mov_b32 s47, -2
	s_waitcnt lgkmcnt(0)

;     __device__ __forceinline__ bool next(int i, Unit& u) const {
;         const int nwg = nM * nN; const long L = (long)i * G + c; if (L >= nwg) return false;
;         int wgid = (int)L; { const int q = nwg / NXCD, r = nwg % NXCD, xcd = wgid % NXCD, off = wgid / NXCD; wgid = (xcd < r ? xcd * (q + 1) : r * (q + 1) + (xcd - r) * q) + off; }
;         const int nig = WGM * nN, gid = wgid / nig, fm = gid * WGM, gsz = (nM - fm) < WGM ? (nM - fm) : WGM;
;         u.pm = fm + ((wgid % nig) % gsz); u.pn = (wgid % nig) / gsz; return true;
; template <class PT, class Epi>
; __device__ __forceinline__ void gemm_phase_once(LAS unsigned char* lds, const PT& S, const Epi& E, bool epi_on) {
;     ...
; #pragma unroll
;         for (int a = 0; a < 2; ++a)
; #pragma unroll
;             for (int b = 0; b < 2; ++b)
; #pragma unroll
;                 for (int m = 0; m < 4; ++m)
; #pragma unroll
;                     for (int n = 0; n < 2; ++n) acc[a][b][m][n] = (f32x4){0.f, 0.f, 0.f, 0.f};
.LBB0_2415:
	s_add_i32 s34, s34, 1
	s_mul_i32 s0, s34, s37
	s_mul_hi_u32 s1, s34, s33
	v_mov_b32_e32 v4, 0
	v_mov_b32_e32 v5, 0
	v_mov_b32_e32 v6, 0
	v_mov_b32_e32 v7, 0
	s_nop 1
	v_mfma_f32_16x16x32_bf16 v[8:11], v[4:7], v[4:7], 0
	v_mfma_f32_16x16x32_bf16 v[12:15], v[4:7], v[4:7], 0
	v_mfma_f32_16x16x32_bf16 v[16:19], v[4:7], v[4:7], 0
	v_mfma_f32_32x32x16_bf16 v[20:35], v[4:7], v[4:7], 0
	v_mfma_f32_32x32x16_bf16 v[36:51], v[4:7], v[4:7], 0
	v_mfma_f32_32x32x16_bf16 v[52:67], v[4:7], v[4:7], 0
	v_mfma_f32_32x32x16_bf16 v[68:83], v[4:7], v[4:7], 0
	v_mfma_f32_32x32x16_bf16 v[84:99], v[4:7], v[4:7], 0
	v_mfma_f32_32x32x16_bf16 v[100:115], v[4:7], v[4:7], 0
	v_mfma_f32_32x32x16_bf16 v[116:131], v[4:7], v[4:7], 0
	s_add_i32 s1, s1, s0
	s_mul_i32 s0, s34, s33
	v_readlane_b32 s11, v254, 9
	s_add_u32 s16, s0, s11
	s_addc_u32 s17, s1, s27
	v_cmp_gt_i64_e64 s[0:1], s[16:17], v[146:147]
	s_and_b64 vcc, exec, s[0:1]
	s_cbranch_vccnz .LBB0_2421
	s_ashr_i32 s10, s16, 31
	s_lshr_b32 s10, s10, 29
	s_add_i32 s14, s16, s10
	s_and_b32 s10, s14, -8
	s_sub_i32 s15, s16, s10
	s_cmp_gt_i32 s15, -1
	s_mov_b64 s[10:11], -1
	s_cbranch_scc0 .LBB0_2418
	s_lshl_b32 s18, s15, 6
	s_mov_b64 s[10:11], 0

;     __device__ __forceinline__ const char* pa(const Unit& u) const { return (const char*)(A + (size_t)u.pm * a_tile_stride + (size_t)u.pn * 512); }
;     __device__ __forceinline__ bool next(int i, Unit& u) const {
;     ...
;         const int nig = WGM * nN, gid = wgid / nig, fm = gid * WGM, gsz = (nM - fm) < WGM ? (nM - fm) : WGM;
;         u.pm = fm + ((wgid % nig) % gsz); u.pn = (wgid % nig) / gsz; return true;
;     }
;     __device__ __forceinline__ const char* pa(const Unit& u) const { return (const char*)(A + (size_t)u.pm * a_tile_stride + (size_t)((u.pn >> a_group_shift) * a_group_cols)); }
;     __device__ __forceinline__ const char* pb(const Unit& u) const { return (const char*)(Bt + (size_t)u.pn * b_tile_stride); }
; template <class PT, class Epi>
; __device__ __forceinline__ void gemm_phase_once(LAS unsigned char* lds, const PT& S, const Epi& E, bool epi_on) {
;     ...
;         const bool has_next = S.next(ui + 1, nxt);
;         const char* nA = has_next ? S.pa(nxt) : cA; const char* nB = has_next ? S.pb(nxt) : cB;
;         for (int t = 0; t < nt; t += 2) {
;             const bool last = (t == nt - 2);
;             const char* a1 = cA + (size_t)(t + 1) * kstep;
;             const char* a2 = last ? nA : cA + (size_t)(t + 2) * kstep; const char* b2 = last ? nB : cB + (size_t)(t + 2) * kstep;
;             const char* a3 = a2 + kstep; const char* b3 = b2 + kstep;
.LBB0_2420:
	s_ashr_i32 s10, s14, 3
	s_add_i32 s10, s18, s10
	s_ashr_i32 s11, s10, 31
	s_lshr_b32 s11, s11, 26
	s_add_i32 s11, s10, s11
	s_ashr_i32 s14, s11, 6
	s_lshl_b32 s14, s14, 3
	s_sub_i32 s15, 64, s14
	s_min_i32 s15, s15, 8
	s_abs_i32 s18, s15
	v_cvt_f32_u32_e32 v153, s18
	s_sub_i32 s24, 0, s18
	s_andn2_b32 s11, s11, 63
	s_sub_i32 s11, s10, s11
	v_rcp_iflag_f32_e32 v153, v153
	s_abs_i32 s10, s11
	s_xor_b32 s19, s11, s15
	s_ashr_i32 s19, s19, 31
	v_mul_f32_e32 v153, 0x4f7ffffe, v153
	v_cvt_u32_f32_e32 v153, v153
	s_nop 0
	v_readfirstlane_b32 s25, v153
	s_mul_i32 s24, s24, s25
	s_mul_hi_u32 s24, s25, s24
	s_add_i32 s25, s25, s24
	s_mul_hi_u32 s24, s10, s25
	s_mul_i32 s25, s24, s18
	s_sub_i32 s10, s10, s25
	s_add_i32 s41, s24, 1
	s_sub_i32 s25, s10, s18
	s_cmp_ge_u32 s10, s18
	s_cselect_b32 s24, s41, s24
	s_cselect_b32 s10, s25, s10
	s_add_i32 s25, s24, 1
	s_cmp_ge_u32 s10, s18
	s_cselect_b32 s10, s25, s24
	s_xor_b32 s10, s10, s19
	s_sub_i32 s10, s10, s19
	s_mul_i32 s15, s10, s15
	s_sub_i32 s11, s11, s15
	s_add_i32 s14, s14, s11
.LBB0_2421:
	s_ashr_i32 s15, s14, 31
	v_cmp_lt_i64_e32 vcc, s[16:17], v[144:145]
	s_lshl_b64 s[16:17], s[14:15], 20
	s_add_u32 s16, s78, s16
	s_addc_u32 s17, s79, s17
	s_and_b64 s[18:19], vcc, exec
	s_cselect_b32 s15, s17, s21
	s_cselect_b32 s41, s16, s20
	s_ashr_i32 s11, s10, 31
	s_lshl_b64 s[18:19], s[10:11], 20
	s_add_u32 s18, s92, s18
	s_addc_u32 s19, s93, s19
	s_and_b64 s[24:25], vcc, exec
	s_cselect_b32 s11, s19, s23
	s_cselect_b32 s42, s18, s22
	s_add_u32 s20, s20, 0x80080
	s_addc_u32 s21, s21, 0
	s_add_u32 s43, s22, 0x100
	s_addc_u32 s44, s23, 0
	s_mov_b32 s45, -2
	s_waitcnt lgkmcnt(0)

;     __device__ __forceinline__ bool next(int i, Unit& u) const {
;         const int nwg = nM * nN; const long L = (long)i * G + c; if (L >= nwg) return false;
;         int wgid = (int)L; { const int q = nwg / NXCD, r = nwg % NXCD, xcd = wgid % NXCD, off = wgid / NXCD; wgid = (xcd < r ? xcd * (q + 1) : r * (q + 1) + (xcd - r) * q) + off; }
;         const int nig = WGM * nN, gid = wgid / nig, fm = gid * WGM, gsz = (nM - fm) < WGM ? (nM - fm) : WGM;
;         u.pm = fm + ((wgid % nig) % gsz); u.pn = (wgid % nig) / gsz; return true;
; template <class PT, class Epi>
; __device__ __forceinline__ void gemm_phase_once(LAS unsigned char* lds, const PT& S, const Epi& E, bool epi_on) {
;     ...
; #pragma unroll
;         for (int a = 0; a < 2; ++a)
; #pragma unroll
;             for (int b = 0; b < 2; ++b)
; #pragma unroll
;                 for (int m = 0; m < 4; ++m)
; #pragma unroll
;                     for (int n = 0; n < 2; ++n) acc[a][b][m][n] = (f32x4){0.f, 0.f, 0.f, 0.f};
.LBB0_2549:
	s_add_i32 s34, s34, 1
	s_mul_i32 s0, s34, s37
	s_mul_hi_u32 s1, s34, s33
	v_mov_b32_e32 v4, 0
	v_mov_b32_e32 v5, 0
	v_mov_b32_e32 v6, 0
	v_mov_b32_e32 v7, 0
	s_nop 1
	v_mfma_f32_16x16x32_bf16 v[8:11], v[4:7], v[4:7], 0
	v_mfma_f32_16x16x32_bf16 v[12:15], v[4:7], v[4:7], 0
	v_mfma_f32_16x16x32_bf16 v[16:19], v[4:7], v[4:7], 0
	v_mfma_f32_32x32x16_bf16 v[20:35], v[4:7], v[4:7], 0
	v_mfma_f32_32x32x16_bf16 v[36:51], v[4:7], v[4:7], 0
	v_mfma_f32_32x32x16_bf16 v[52:67], v[4:7], v[4:7], 0
	v_mfma_f32_32x32x16_bf16 v[68:83], v[4:7], v[4:7], 0
	v_mfma_f32_32x32x16_bf16 v[84:99], v[4:7], v[4:7], 0
	v_mfma_f32_32x32x16_bf16 v[100:115], v[4:7], v[4:7], 0
	v_mfma_f32_32x32x16_bf16 v[116:131], v[4:7], v[4:7], 0
	s_add_i32 s1, s1, s0
	s_mul_i32 s0, s34, s33
	v_readlane_b32 s11, v254, 9
	s_add_u32 s14, s0, s11
	s_addc_u32 s15, s1, s27
	v_cmp_gt_i64_e64 s[0:1], s[14:15], v[146:147]
	s_and_b64 vcc, exec, s[0:1]
	s_cbranch_vccnz .LBB0_2555
	s_ashr_i32 s10, s14, 31
	s_lshr_b32 s10, s10, 29
	s_add_i32 s12, s14, s10
	s_and_b32 s10, s12, -8
	s_sub_i32 s13, s14, s10
	s_cmp_gt_i32 s13, -1
	s_mov_b64 s[10:11], -1
	s_cbranch_scc0 .LBB0_2552
	s_lshl_b32 s16, s13, 4
	s_mov_b64 s[10:11], 0

;     __device__ __forceinline__ const char* pa(const Unit& u) const { return (const char*)(A + (size_t)u.pm * a_tile_stride + (size_t)u.pn * 512); }
;     __device__ __forceinline__ bool next(int i, Unit& u) const {
;     ...
;         const int nig = WGM * nN, gid = wgid / nig, fm = gid * WGM, gsz = (nM - fm) < WGM ? (nM - fm) : WGM;
;         u.pm = fm + ((wgid % nig) % gsz); u.pn = (wgid % nig) / gsz; return true;
;     }
;     __device__ __forceinline__ const char* pa(const Unit& u) const { return (const char*)(A + (size_t)u.pm * a_tile_stride + (size_t)((u.pn >> a_group_shift) * a_group_cols)); }
;     __device__ __forceinline__ const char* pb(const Unit& u) const { return (const char*)(Bt + (size_t)u.pn * b_tile_stride); }
; template <class PT, class Epi>
; __device__ __forceinline__ void gemm_phase_once(LAS unsigned char* lds, const PT& S, const Epi& E, bool epi_on) {
;     ...
;         const bool has_next = S.next(ui + 1, nxt);
;         const char* nA = has_next ? S.pa(nxt) : cA; const char* nB = has_next ? S.pb(nxt) : cB;
;         for (int t = 0; t < nt; t += 2) {
;             const bool last = (t == nt - 2);
;             const char* a1 = cA + (size_t)(t + 1) * kstep;
;             const char* a2 = last ? nA : cA + (size_t)(t + 2) * kstep; const char* b2 = last ? nB : cB + (size_t)(t + 2) * kstep;
;             const char* a3 = a2 + kstep; const char* b3 = b2 + kstep;
.LBB0_2554:
	s_ashr_i32 s10, s12, 3
	s_add_i32 s10, s16, s10
	s_ashr_i32 s11, s10, 31
	s_lshr_b32 s11, s11, 28
	s_add_i32 s11, s10, s11
	s_ashr_i32 s12, s11, 4
	s_lshl_b32 s12, s12, 3
	s_sub_i32 s13, 64, s12
	s_min_i32 s13, s13, 8
	s_abs_i32 s16, s13
	v_cvt_f32_u32_e32 v165, s16
	s_sub_i32 s24, 0, s16
	s_and_b32 s11, s11, -16
	s_sub_i32 s11, s10, s11
	v_rcp_iflag_f32_e32 v165, v165
	s_abs_i32 s10, s11
	s_xor_b32 s17, s11, s13
	s_ashr_i32 s17, s17, 31
	v_mul_f32_e32 v165, 0x4f7ffffe, v165
	v_cvt_u32_f32_e32 v165, v165
	s_nop 0
	v_readfirstlane_b32 s25, v165
	s_mul_i32 s24, s24, s25
	s_mul_hi_u32 s24, s25, s24
	s_add_i32 s25, s25, s24
	s_mul_hi_u32 s24, s10, s25
	s_mul_i32 s25, s24, s16
	s_sub_i32 s10, s10, s25
	s_add_i32 s41, s24, 1
	s_sub_i32 s25, s10, s16
	s_cmp_ge_u32 s10, s16
	s_cselect_b32 s24, s41, s24
	s_cselect_b32 s10, s25, s10
	s_add_i32 s25, s24, 1
	s_cmp_ge_u32 s10, s16
	s_cselect_b32 s10, s25, s24
	s_xor_b32 s10, s10, s17
	s_sub_i32 s10, s10, s17
	s_mul_i32 s13, s10, s13
	s_sub_i32 s11, s11, s13
	s_add_i32 s12, s12, s11
.LBB0_2555:
	s_ashr_i32 s13, s12, 31
	v_cmp_lt_i64_e32 vcc, s[14:15], v[144:145]
	s_lshl_b64 s[14:15], s[12:13], 20
	s_add_u32 s14, s72, s14
	s_addc_u32 s15, s73, s15
	s_and_b64 s[16:17], vcc, exec
	s_cselect_b32 s13, s15, s21
	s_cselect_b32 s41, s14, s20
	s_ashr_i32 s11, s10, 31
	s_lshl_b64 s[16:17], s[10:11], 20
	s_add_u32 s16, s84, s16
	s_addc_u32 s17, s85, s17
	s_and_b64 s[24:25], vcc, exec
	s_cselect_b32 s11, s17, s23
	s_cselect_b32 s42, s16, s22
	s_add_u32 s20, s20, 0x80080
	s_addc_u32 s21, s21, 0
	s_add_u32 s43, s22, 0x100
	s_addc_u32 s44, s23, 0
	s_mov_b32 s45, -2
	s_waitcnt lgkmcnt(0)
	s_waitcnt vmcnt(0)

;     __device__ __forceinline__ bool next(int i, Unit& u) const {
;         const int nwg = nM * nN; const long L = (long)i * G + c; if (L >= nwg) return false;
;         int wgid = (int)L; { const int q = nwg / NXCD, r = nwg % NXCD, xcd = wgid % NXCD, off = wgid / NXCD; wgid = (xcd < r ? xcd * (q + 1) : r * (q + 1) + (xcd - r) * q) + off; }
;         const int nig = WGM * nN, gid = wgid / nig, fm = gid * WGM, gsz = (nM - fm) < WGM ? (nM - fm) : WGM;
;         u.pm = fm + ((wgid % nig) % gsz); u.pn = (wgid % nig) / gsz; return true;
; template <class PT, class Epi>
; __device__ __forceinline__ void gemm_phase_once(LAS unsigned char* lds, const PT& S, const Epi& E, bool epi_on) {
;     ...
; #pragma unroll
;         for (int a = 0; a < 2; ++a)
; #pragma unroll
;             for (int b = 0; b < 2; ++b)
; #pragma unroll
;                 for (int m = 0; m < 4; ++m)
; #pragma unroll
;                     for (int n = 0; n < 2; ++n) acc[a][b][m][n] = (f32x4){0.f, 0.f, 0.f, 0.f};
.LBB0_2572:
	s_add_i32 s37, s37, 1
	s_mul_i32 s1, s37, s41
	s_mul_hi_u32 s10, s37, s33
	v_mov_b32_e32 v4, 0
	v_mov_b32_e32 v5, 0
	v_mov_b32_e32 v6, 0
	v_mov_b32_e32 v7, 0
	s_nop 1
	v_mfma_f32_16x16x32_bf16 v[8:11], v[4:7], v[4:7], 0
	v_mfma_f32_16x16x32_bf16 v[12:15], v[4:7], v[4:7], 0
	v_mfma_f32_16x16x32_bf16 v[16:19], v[4:7], v[4:7], 0
	v_mfma_f32_32x32x16_bf16 v[20:35], v[4:7], v[4:7], 0
	v_mfma_f32_32x32x16_bf16 v[36:51], v[4:7], v[4:7], 0
	v_mfma_f32_32x32x16_bf16 v[52:67], v[4:7], v[4:7], 0
	v_mfma_f32_32x32x16_bf16 v[68:83], v[4:7], v[4:7], 0
	v_mfma_f32_32x32x16_bf16 v[84:99], v[4:7], v[4:7], 0
	v_mfma_f32_32x32x16_bf16 v[100:115], v[4:7], v[4:7], 0
	v_mfma_f32_32x32x16_bf16 v[116:131], v[4:7], v[4:7], 0
	s_add_i32 s10, s10, s1
	s_mul_i32 s1, s37, s33
	s_add_u32 s16, s1, s28
	s_addc_u32 s17, s10, s42
	v_cmp_gt_i64_e64 s[10:11], s[16:17], 15
	s_and_b64 vcc, exec, s[10:11]
	s_cbranch_vccnz .LBB0_2578
	s_ashr_i32 s1, s16, 31
	s_lshr_b32 s1, s1, 29
	s_add_i32 s1, s16, s1
	s_and_b32 s12, s1, -8
	s_sub_i32 s14, s16, s12
	s_cmp_gt_i32 s14, -1
	s_mov_b64 s[12:13], -1
	s_cbranch_scc0 .LBB0_2575
	s_lshl_b32 s15, s14, 1
	s_mov_b64 s[12:13], 0

;     __device__ __forceinline__ const char* pa(const Unit& u) const { return (const char*)(A + (size_t)u.pm * a_tile_stride + (size_t)u.pn * 512); }
;     __device__ __forceinline__ bool next(int i, Unit& u) const {
;     ...
;         const int nig = WGM * nN, gid = wgid / nig, fm = gid * WGM, gsz = (nM - fm) < WGM ? (nM - fm) : WGM;
;         u.pm = fm + ((wgid % nig) % gsz); u.pn = (wgid % nig) / gsz; return true;
;     }
;     __device__ __forceinline__ const char* pa(const Unit& u) const { return (const char*)(A + (size_t)u.pm * a_tile_stride + (size_t)((u.pn >> a_group_shift) * a_group_cols)); }
;     __device__ __forceinline__ const char* pb(const Unit& u) const { return (const char*)(Bt + (size_t)u.pn * b_tile_stride); }
; template <class PT, class Epi>
; __device__ __forceinline__ void gemm_phase_once(LAS unsigned char* lds, const PT& S, const Epi& E, bool epi_on) {
;     ...
;         const bool has_next = S.next(ui + 1, nxt);
;         const char* nA = has_next ? S.pa(nxt) : cA; const char* nB = has_next ? S.pb(nxt) : cB;
;         for (int t = 0; t < nt; t += 2) {
;             const bool last = (t == nt - 2);
;             const char* a1 = cA + (size_t)(t + 1) * kstep;
;             const char* a2 = last ? nA : cA + (size_t)(t + 2) * kstep; const char* b2 = last ? nB : cB + (size_t)(t + 2) * kstep;
;             const char* a3 = a2 + kstep; const char* b3 = b2 + kstep;
.LBB0_2577:
	s_ashr_i32 s1, s1, 3
	s_add_i32 s1, s15, s1
	s_ashr_i32 s12, s1, 31
	s_lshr_b32 s12, s12, 27
	s_add_i32 s12, s1, s12
	s_ashr_i32 s13, s12, 5
	s_lshl_b32 s13, s13, 3
	s_sub_i32 s14, 4, s13
	s_min_i32 s14, s14, 8
	s_abs_i32 s15, s14
	v_cvt_f32_u32_e32 v140, s15
	s_sub_i32 s19, 0, s15
	s_andn2_b32 s12, s12, 31
	s_sub_i32 s1, s1, s12
	v_rcp_iflag_f32_e32 v140, v140
	s_abs_i32 s12, s1
	s_xor_b32 s18, s1, s14
	s_ashr_i32 s18, s18, 31
	v_mul_f32_e32 v140, 0x4f7ffffe, v140
	v_cvt_u32_f32_e32 v140, v140
	s_nop 0
	v_readfirstlane_b32 s21, v140
	s_mul_i32 s19, s19, s21
	s_mul_hi_u32 s19, s21, s19
	s_add_i32 s21, s21, s19
	s_mul_hi_u32 s19, s12, s21
	s_mul_i32 s21, s19, s15
	s_sub_i32 s12, s12, s21
	s_add_i32 s26, s19, 1
	s_sub_i32 s21, s12, s15
	s_cmp_ge_u32 s12, s15
	s_cselect_b32 s19, s26, s19
	s_cselect_b32 s12, s21, s12
	s_add_i32 s21, s19, 1
	s_cmp_ge_u32 s12, s15
	s_cselect_b32 s12, s21, s19
	s_xor_b32 s12, s12, s18
	s_sub_i32 s12, s12, s18
	s_mul_i32 s14, s12, s14
	s_sub_i32 s1, s1, s14
	s_add_i32 s14, s13, s1
.LBB0_2578:
	s_ashr_i32 s15, s14, 31
	v_cmp_lt_i64_e64 s[26:27], s[16:17], 16
	s_lshl_b64 s[16:17], s[14:15], 20
	s_add_u32 s16, s81, s16
	s_addc_u32 s17, s96, s17
	s_and_b64 s[18:19], s[26:27], exec
	s_cselect_b32 s1, s17, s23
	s_cselect_b32 s15, s16, s22
	s_ashr_i32 s13, s12, 31
	s_lshl_b64 s[18:19], s[12:13], 20
	s_add_u32 s18, s82, s18
	s_addc_u32 s19, s83, s19
	s_and_b64 s[26:27], s[26:27], exec
	s_cselect_b32 s13, s19, s25
	s_cselect_b32 s21, s18, s24
	s_add_u32 s22, s22, 0x80080
	s_addc_u32 s23, s23, 0
	s_add_u32 s47, s24, 0x100
	s_addc_u32 s48, s25, 0
	s_mov_b32 s49, -2
	s_waitcnt lgkmcnt(0)

;     __device__ __forceinline__ const char* pa(const Unit& u) const { return (const char*)(A + (size_t)u.pm * a_tile_stride + (size_t)u.pn * 512); }
;     __device__ __forceinline__ const char* pa(const Unit& u) const { return (const char*)(A + (size_t)u.pm * a_tile_stride + (size_t)((u.pn >> a_group_shift) * a_group_cols)); }
;     __device__ __forceinline__ const char* pb(const Unit& u) const { return (const char*)(Bt + (size_t)u.pn * b_tile_stride); }
; template <class PT, class Epi>
; __device__ __forceinline__ void gemm_phase_once(LAS unsigned char* lds, const PT& S, const Epi& E, bool epi_on) {
;     ...
;         const bool has_next = S.next(ui + 1, nxt);
;         const char* nA = has_next ? S.pa(nxt) : cA; const char* nB = has_next ? S.pb(nxt) : cB;
;         for (int t = 0; t < nt; t += 2) {
;             const bool last = (t == nt - 2);
;             const char* a1 = cA + (size_t)(t + 1) * kstep;
;             const char* a2 = last ? nA : cA + (size_t)(t + 2) * kstep; const char* b2 = last ? nB : cB + (size_t)(t + 2) * kstep;
;             const char* a3 = a2 + kstep; const char* b3 = b2 + kstep;
.LBB0_2855:
	s_ashr_i32 s15, s14, 31
	v_cmp_lt_i64_e32 vcc, s[16:17], v[144:145]
	s_lshl_b64 s[16:17], s[14:15], 18
	v_readlane_b32 s18, v254, 48
	v_readlane_b32 s19, v254, 49
	s_add_u32 s16, s18, s16
	s_addc_u32 s17, s19, s17
	s_and_b64 s[18:19], vcc, exec
	s_cselect_b32 s15, s17, s21
	s_cselect_b32 s41, s16, s20
	s_ashr_i32 s11, s10, 31
	s_lshl_b64 s[18:19], s[10:11], 18
	v_readlane_b32 s24, v254, 7
	v_readlane_b32 s25, v254, 8
	s_add_u32 s18, s24, s18
	s_addc_u32 s19, s25, s19
	s_and_b64 s[24:25], vcc, exec
	s_cselect_b32 s11, s19, s23
	s_cselect_b32 s42, s18, s22
	s_add_u32 s20, s20, 0x20080
	s_addc_u32 s21, s21, 0
	s_add_u32 s43, s22, 0x100
	s_addc_u32 s44, s23, 0
	s_mov_b32 s45, -2
	s_waitcnt lgkmcnt(0)

;     __device__ __forceinline__ const char* pa(const Unit& u) const { return (const char*)(A + (size_t)u.pm * a_tile_stride + (size_t)u.pn * 512); }
;     __device__ __forceinline__ bool next(int i, Unit& u) const {
;         const int nwg = nM * nN; const long L = (long)i * G + c; if (L >= nwg) return false;
;         int wgid = (int)L; { const int q = nwg / NXCD, r = nwg % NXCD, xcd = wgid % NXCD, off = wgid / NXCD; wgid = (xcd < r ? xcd * (q + 1) : r * (q + 1) + (xcd - r) * q) + off; }
;         const int nig = WGM * nN, gid = wgid / nig, fm = gid * WGM, gsz = (nM - fm) < WGM ? (nM - fm) : WGM;
;         u.pm = fm + ((wgid % nig) % gsz); u.pn = (wgid % nig) / gsz; return true;
;     }
;     __device__ __forceinline__ const char* pa(const Unit& u) const { return (const char*)(A + (size_t)u.pm * a_tile_stride + (size_t)((u.pn >> a_group_shift) * a_group_cols)); }
;     __device__ __forceinline__ const char* pb(const Unit& u) const { return (const char*)(Bt + (size_t)u.pn * b_tile_stride); }
; template <class PT, class Epi>
; __device__ __forceinline__ void gemm_phase_once(LAS unsigned char* lds, const PT& S, const Epi& E, bool epi_on) {
;     ...
; #pragma unroll
;         for (int a = 0; a < 2; ++a)
; #pragma unroll
;             for (int b = 0; b < 2; ++b)
; #pragma unroll
;                 for (int m = 0; m < 4; ++m)
; #pragma unroll
;                     for (int n = 0; n < 2; ++n) acc[a][b][m][n] = (f32x4){0.f, 0.f, 0.f, 0.f};
.LBB0_2980:
	s_add_i32 s55, s55, 1
	s_mul_i32 s0, s55, s58
	s_mul_hi_u32 s1, s55, s33
	v_mov_b32_e32 v4, 0
	v_mov_b32_e32 v5, 0
	v_mov_b32_e32 v6, 0
	v_mov_b32_e32 v7, 0
	s_nop 1
	v_mfma_f32_16x16x32_bf16 v[8:11], v[4:7], v[4:7], 0
	v_mfma_f32_16x16x32_bf16 v[12:15], v[4:7], v[4:7], 0
	v_mfma_f32_16x16x32_bf16 v[16:19], v[4:7], v[4:7], 0
	v_mfma_f32_32x32x16_bf16 v[20:35], v[4:7], v[4:7], 0
	v_mfma_f32_32x32x16_bf16 v[44:59], v[4:7], v[4:7], 0
	v_mfma_f32_32x32x16_bf16 v[60:75], v[4:7], v[4:7], 0
	v_mfma_f32_32x32x16_bf16 v[76:91], v[4:7], v[4:7], 0
	v_mfma_f32_32x32x16_bf16 v[92:107], v[4:7], v[4:7], 0
	v_mfma_f32_32x32x16_bf16 v[108:123], v[4:7], v[4:7], 0
	v_mfma_f32_32x32x16_bf16 v[124:139], v[4:7], v[4:7], 0
	s_add_i32 s1, s1, s0
	s_mul_i32 s0, s55, s33
	v_readlane_b32 s27, v254, 9
	s_add_u32 s30, s0, s27
	s_addc_u32 s31, s1, s49
	v_cmp_gt_i64_e64 s[0:1], s[30:31], v[156:157]
	s_and_b64 vcc, exec, s[0:1]
	s_cbranch_vccnz .LBB0_2982
	s_ashr_i32 s26, s30, 31
	s_lshr_b32 s26, s26, 29
	s_add_i32 s26, s30, s26
	s_ashr_i32 s27, s26, 3
	s_and_b32 s26, s26, -8
	s_sub_i32 s26, s30, s26
	s_cmp_lt_i32 s26, 0
	s_cselect_b32 s28, s50, 0x160
	s_mul_i32 s26, s28, s26
	s_add_i32 s26, s26, s27
	s_mul_hi_i32 s27, s26, 0x2e8ba2e9
	s_lshr_b32 s28, s27, 31
	s_ashr_i32 s27, s27, 6
	s_add_i32 s27, s27, s28
	s_lshl_b32 s28, s27, 3
	s_sub_i32 s29, 64, s28
	s_min_i32 s29, s29, 8
	s_abs_i32 s34, s29
	v_cvt_f32_u32_e32 v40, s34
	s_sub_i32 s37, 0, s34
	s_mulk_i32 s27, 0x160
	s_sub_i32 s27, s26, s27
	v_rcp_iflag_f32_e32 v40, v40
	s_abs_i32 s26, s27
	s_xor_b32 s35, s27, s29
	s_ashr_i32 s35, s35, 31
	v_mul_f32_e32 v40, 0x4f7ffffe, v40
	v_cvt_u32_f32_e32 v40, v40
	s_nop 0
	v_readfirstlane_b32 s42, v40
	s_mul_i32 s37, s37, s42
	s_mul_hi_u32 s37, s42, s37
	s_add_i32 s42, s42, s37
	s_mul_hi_u32 s37, s26, s42
	s_mul_i32 s42, s37, s34
	s_sub_i32 s26, s26, s42
	s_add_i32 s43, s37, 1
	s_sub_i32 s42, s26, s34
	s_cmp_ge_u32 s26, s34
	s_cselect_b32 s37, s43, s37
	s_cselect_b32 s26, s42, s26
	s_add_i32 s42, s37, 1
	s_cmp_ge_u32 s26, s34
	s_cselect_b32 s26, s42, s37
	s_xor_b32 s26, s26, s35
	s_sub_i32 s26, s26, s35
	s_mul_i32 s29, s26, s29
	s_sub_i32 s27, s27, s29
	s_add_i32 s28, s27, s28
.LBB0_2982:
	s_ashr_i32 s29, s28, 31
	v_cmp_lt_i64_e32 vcc, s[30:31], v[154:155]
	s_lshl_b64 s[30:31], s[28:29], 20
	s_add_u32 s30, s72, s30
	s_addc_u32 s31, s73, s31
	s_and_b64 s[34:35], vcc, exec
	s_cselect_b32 s29, s31, s39
	s_cselect_b32 s37, s30, s38
	s_ashr_i32 s27, s26, 31
	s_lshl_b64 s[34:35], s[26:27], 20
	s_add_u32 s34, s76, s34
	s_addc_u32 s35, s77, s35
	s_and_b64 s[42:43], vcc, exec
	s_cselect_b32 s27, s35, s41
	s_cselect_b32 s64, s34, s40
	s_add_u32 s65, s40, 0x100
	s_addc_u32 s66, s41, 0
	s_mov_b32 s67, -2
	s_waitcnt lgkmcnt(0)
	s_waitcnt vmcnt(0)

;     __device__ __forceinline__ bool next(int i, Unit& u) const {
;         const int nwg = nM * nN; const long L = (long)i * G + c; if (L >= nwg) return false;
;         int wgid = (int)L; { const int q = nwg / NXCD, r = nwg % NXCD, xcd = wgid % NXCD, off = wgid / NXCD; wgid = (xcd < r ? xcd * (q + 1) : r * (q + 1) + (xcd - r) * q) + off; }
;         const int nig = WGM * nN, gid = wgid / nig, fm = gid * WGM, gsz = (nM - fm) < WGM ? (nM - fm) : WGM;
;         u.pm = fm + ((wgid % nig) % gsz); u.pn = (wgid % nig) / gsz; return true;
; template <class PT, class Epi>
; __device__ __forceinline__ void gemm_phase_once(LAS unsigned char* lds, const PT& S, const Epi& E, bool epi_on) {
;     ...
; #pragma unroll
;         for (int a = 0; a < 2; ++a)
; #pragma unroll
;             for (int b = 0; b < 2; ++b)
; #pragma unroll
;                 for (int m = 0; m < 4; ++m)
; #pragma unroll
;                     for (int n = 0; n < 2; ++n) acc[a][b][m][n] = (f32x4){0.f, 0.f, 0.f, 0.f};
.LBB0_3131:
	s_add_i32 s27, s27, 1
	s_mul_i32 s0, s27, s30
	s_mul_hi_u32 s1, s27, s33
	v_mov_b32_e32 v4, 0
	v_mov_b32_e32 v5, 0
	v_mov_b32_e32 v6, 0
	v_mov_b32_e32 v7, 0
	s_nop 1
	v_mfma_f32_16x16x32_bf16 v[8:11], v[4:7], v[4:7], 0
	v_mfma_f32_16x16x32_bf16 v[12:15], v[4:7], v[4:7], 0
	v_mfma_f32_16x16x32_bf16 v[16:19], v[4:7], v[4:7], 0
	v_mfma_f32_32x32x16_bf16 v[20:35], v[4:7], v[4:7], 0
	v_mfma_f32_32x32x16_bf16 v[36:51], v[4:7], v[4:7], 0
	v_mfma_f32_32x32x16_bf16 v[52:67], v[4:7], v[4:7], 0
	v_mfma_f32_32x32x16_bf16 v[68:83], v[4:7], v[4:7], 0
	v_mfma_f32_32x32x16_bf16 v[84:99], v[4:7], v[4:7], 0
	v_mfma_f32_32x32x16_bf16 v[100:115], v[4:7], v[4:7], 0
	v_mfma_f32_32x32x16_bf16 v[116:131], v[4:7], v[4:7], 0
	s_add_i32 s1, s1, s0
	s_mul_i32 s0, s27, s33
	v_readlane_b32 s6, v254, 9
	s_add_u32 s8, s0, s6
	s_addc_u32 s9, s1, s21
	v_cmp_gt_i64_e64 s[0:1], s[8:9], v[146:147]
	v_cmp_lt_i64_e64 s[6:7], s[8:9], v[144:145]
	s_and_b64 vcc, exec, s[0:1]
	s_cbranch_vccnz .LBB0_3137
	s_ashr_i32 s9, s8, 31
	s_lshr_b32 s9, s9, 29
	s_add_i32 s18, s8, s9
	s_and_b32 s9, s18, -8
	s_sub_i32 s19, s8, s9
	s_cmp_gt_i32 s19, -1
	s_mov_b64 s[8:9], -1
	s_cbranch_scc0 .LBB0_3134
	s_lshl_b32 s35, s19, 6
	s_mov_b64 s[8:9], 0

;     __device__ __forceinline__ const char* pa(const Unit& u) const { return (const char*)(A + (size_t)u.pm * a_tile_stride + (size_t)u.pn * 512); }
;     __device__ __forceinline__ bool next(int i, Unit& u) const {
;     ...
;         const int nig = WGM * nN, gid = wgid / nig, fm = gid * WGM, gsz = (nM - fm) < WGM ? (nM - fm) : WGM;
;         u.pm = fm + ((wgid % nig) % gsz); u.pn = (wgid % nig) / gsz; return true;
;     }
;     __device__ __forceinline__ const char* pa(const Unit& u) const { return (const char*)(A + (size_t)u.pm * a_tile_stride + (size_t)((u.pn >> a_group_shift) * a_group_cols)); }
;     __device__ __forceinline__ const char* pb(const Unit& u) const { return (const char*)(Bt + (size_t)u.pn * b_tile_stride); }
; template <class PT, class Epi>
; __device__ __forceinline__ void gemm_phase_once(LAS unsigned char* lds, const PT& S, const Epi& E, bool epi_on) {
;     ...
;         const bool has_next = S.next(ui + 1, nxt);
;         const char* nA = has_next ? S.pa(nxt) : cA; const char* nB = has_next ? S.pb(nxt) : cB;
.LBB0_3136:
	s_ashr_i32 s8, s18, 3
	s_add_i32 s8, s35, s8
	s_ashr_i32 s9, s8, 31
	s_lshr_b32 s9, s9, 26
	s_add_i32 s9, s8, s9
	s_ashr_i32 s18, s9, 6
	s_lshl_b32 s18, s18, 3
	s_sub_i32 s19, 64, s18
	s_min_i32 s19, s19, 8
	s_abs_i32 s35, s19
	v_cvt_f32_u32_e32 v153, s35
	s_sub_i32 s39, 0, s35
	s_andn2_b32 s9, s9, 63
	s_sub_i32 s8, s8, s9
	v_rcp_iflag_f32_e32 v153, v153
	s_abs_i32 s9, s8
	s_xor_b32 s36, s8, s19
	s_ashr_i32 s36, s36, 31
	v_mul_f32_e32 v153, 0x4f7ffffe, v153
	v_cvt_u32_f32_e32 v153, v153
	s_nop 0
	v_readfirstlane_b32 s40, v153
	s_mul_i32 s39, s39, s40
	s_mul_hi_u32 s39, s40, s39
	s_add_i32 s40, s40, s39
	s_mul_hi_u32 s39, s9, s40
	s_mul_i32 s40, s39, s35
	s_sub_i32 s9, s9, s40
	s_add_i32 s41, s39, 1
	s_sub_i32 s40, s9, s35
	s_cmp_ge_u32 s9, s35
	s_cselect_b32 s39, s41, s39
	s_cselect_b32 s9, s40, s9
	s_add_i32 s40, s39, 1
	s_cmp_ge_u32 s9, s35
	s_cselect_b32 s9, s40, s39
	s_xor_b32 s9, s9, s36
	s_sub_i32 s35, s9, s36
	s_mul_i32 s9, s35, s19
	s_sub_i32 s8, s8, s9
	s_add_i32 s36, s18, s8
.LBB0_3137:
	v_cndmask_b32_e64 v153, 0, 1, s[6:7]
	v_cmp_ne_u32_e64 s[8:9], 1, v153
	s_andn2_b64 vcc, exec, s[6:7]
	s_mov_b64 s[6:7], s[14:15]
	s_cbranch_vccnz .LBB0_3139
	s_mul_i32 s6, s36, 0x2c0000
	s_mul_hi_i32 s7, s36, 0x2c0000
	s_add_u32 s6, s78, s6
	s_addc_u32 s7, s79, s7

; #define PG8_STAGE(bufoff, gbase, voff) do { _Pragma("unroll") for (int _i = 0; _i < 2; ++_i) \
;         __builtin_amdgcn_global_load_lds((const unsigned*)((const char*)(gbase) + (voff)[_i]), (LAS unsigned*)(lds + (bufoff) + ldsw + _i * 8192), 16, 0, 0); } while (0)
; #define PG8_LDA(dst, b, h) do { _Pragma("unroll") for (int m = 0; m < 4; ++m) _Pragma("unroll") for (int k = 0; k < 2; ++k) dst[m][k] = *(const LAS bf16x8*)(lds + PG8_SA(b, h) + aoff + m * 2048 + k * 1024); } while (0)
; #define PG8_LDB(dst, b, h) do { _Pragma("unroll") for (int n = 0; n < 2; ++n) _Pragma("unroll") for (int k = 0; k < 2; ++k) dst[n][k] = *(const LAS bf16x8*)(lds + PG8_SB(b, h) + boff + n * 2048 + k * 1024); } while (0)
; #define PG8_SCHED __builtin_amdgcn_sched_barrier(0)
; template <class PT, class Epi>
; __device__ __forceinline__ void gemm_phase_once(LAS unsigned char* lds, const PT& S, const Epi& E, bool epi_on) {
;     ...
;             const char* a1 = cA + (size_t)(t + 1) * kstep;
;             const char* a2 = last ? nA : cA + (size_t)(t + 2) * kstep; const char* b2 = last ? nB : cB + (size_t)(t + 2) * kstep;
;             const char* a3 = a2 + kstep; const char* b3 = b2 + kstep;
;             PG8_LDB(B0, 0, 0); PG8_SCHED; PG8_LDA(At, 0, 0); PG8_STAGE(PG8_SA(1, 1), a1 + hstepA, voffA);
.LBB0_3141:
	s_add_u32 s14, s14, 0x160080
	s_addc_u32 s15, s15, 0
	s_add_u32 s39, s16, 0x100
	s_addc_u32 s40, s17, 0
	s_mov_b32 s41, -2
	s_waitcnt lgkmcnt(0)

; template <class PT, class Epi>
; __device__ __forceinline__ void gemm_phase_once(LAS unsigned char* lds, const PT& S, const Epi& E, bool epi_on) {
;     ...
; #pragma unroll
;         for (int a = 0; a < 2; ++a)
; #pragma unroll
;             for (int b = 0; b < 2; ++b)
; #pragma unroll
;                 for (int m = 0; m < 4; ++m)
; #pragma unroll
;                     for (int n = 0; n < 2; ++n) acc[a][b][m][n] = (f32x4){0.f, 0.f, 0.f, 0.f};
.LBB0_3450:
	s_mov_b32 s9, s35
	s_add_i32 s35, s35, 1
	s_cmp_gt_u32 s9, 6
	v_mov_b32_e32 v4, 0
	v_mov_b32_e32 v5, 0
	v_mov_b32_e32 v6, 0
	v_mov_b32_e32 v7, 0
	s_nop 1
	v_mfma_f32_16x16x32_bf16 v[8:11], v[4:7], v[4:7], 0
	v_mfma_f32_16x16x32_bf16 v[12:15], v[4:7], v[4:7], 0
	v_mfma_f32_16x16x32_bf16 v[16:19], v[4:7], v[4:7], 0
	v_mfma_f32_32x32x16_bf16 v[20:35], v[4:7], v[4:7], 0
	v_mfma_f32_32x32x16_bf16 v[36:51], v[4:7], v[4:7], 0
	v_mfma_f32_32x32x16_bf16 v[52:67], v[4:7], v[4:7], 0
	v_mfma_f32_32x32x16_bf16 v[68:83], v[4:7], v[4:7], 0
	v_mfma_f32_32x32x16_bf16 v[84:99], v[4:7], v[4:7], 0
	v_mfma_f32_32x32x16_bf16 v[100:115], v[4:7], v[4:7], 0
	v_mfma_f32_32x32x16_bf16 v[116:131], v[4:7], v[4:7], 0
	s_mov_b64 s[24:25], 0
	s_cbranch_scc1 .LBB0_3457
	s_add_i32 s9, s35, s26
	s_lshl_b32 s9, s9, 7
	s_add_i32 s9, s9, s27
	s_cmpk_gt_i32 s9, 0x7ff
	s_cbranch_scc1 .LBB0_3457
	s_ashr_i32 s8, s9, 31
	s_lshr_b32 s8, s8, 29
	s_add_i32 s10, s9, s8
	s_and_b32 s8, s10, -8
	s_sub_i32 s11, s9, s8
	s_cmp_gt_i32 s11, -1
	s_mov_b64 s[8:9], -1
	s_cbranch_scc0 .LBB0_3454
	s_lshl_b32 s12, s11, 8
	s_mov_b64 s[8:9], 0

;     __device__ __forceinline__ const char* pa(const Unit& u) const { return (const char*)(A + (size_t)u.pm * a_tile_stride + (size_t)u.pn * 512); }
;     __device__ __forceinline__ const char* pa(const Unit& u) const { return (const char*)(A + (size_t)u.pm * a_tile_stride + (size_t)((u.pn >> a_group_shift) * a_group_cols)); }
;     __device__ __forceinline__ const char* pb(const Unit& u) const { return (const char*)(Bt + (size_t)u.pn * b_tile_stride); }
; template <class PT, class Epi>
; __device__ __forceinline__ void gemm_phase_once(LAS unsigned char* lds, const PT& S, const Epi& E, bool epi_on) {
;     ...
;         const bool has_next = S.next(ui + 1, nxt);
;         const char* nA = has_next ? S.pa(nxt) : cA; const char* nB = has_next ? S.pb(nxt) : cB;
;         for (int t = 0; t < nt; t += 2) {
;             const bool last = (t == nt - 2);
;             const char* a1 = cA + (size_t)(t + 1) * kstep;
;             const char* a2 = last ? nA : cA + (size_t)(t + 2) * kstep; const char* b2 = last ? nB : cB + (size_t)(t + 2) * kstep;
;             const char* a3 = a2 + kstep; const char* b3 = b2 + kstep;
.LBB0_3457:
	s_ashr_i32 s9, s8, 31
	s_xor_b64 s[14:15], s[24:25], -1
	s_lshl_b64 s[12:13], s[8:9], 20
	s_add_u32 s12, s72, s12
	s_addc_u32 s13, s73, s13
	s_and_b64 s[16:17], s[24:25], exec
	s_cselect_b32 s9, s13, s21
	s_cselect_b32 s41, s12, s20
	s_ashr_i32 s11, s10, 31
	s_lshl_b64 s[16:17], s[10:11], 20
	v_readlane_b32 s42, v254, 5
	v_readlane_b32 s43, v254, 6
	s_add_u32 s16, s42, s16
	s_addc_u32 s17, s43, s17
	s_and_b64 s[24:25], s[24:25], exec
	s_cselect_b32 s11, s17, s23
	s_cselect_b32 s42, s16, s22
	s_add_u32 s20, s20, 0x80080
	s_addc_u32 s21, s21, 0
	s_add_u32 s43, s22, 0x100
	s_addc_u32 s44, s23, 0
	s_mov_b32 s45, -2
	s_waitcnt lgkmcnt(0)
	s_waitcnt vmcnt(0)

;     __device__ __forceinline__ const char* pa(const Unit& u) const { return (const char*)(A + (size_t)u.pm * a_tile_stride + (size_t)u.pn * 512); }
;     __device__ __forceinline__ const char* pa(const Unit& u) const { return (const char*)(A + (size_t)u.pm * a_tile_stride + (size_t)((u.pn >> a_group_shift) * a_group_cols)); }
;     __device__ __forceinline__ const char* pb(const Unit& u) const { return (const char*)(Bt + (size_t)u.pn * b_tile_stride); }
; template <class PT, class Epi>
; __device__ __forceinline__ void gemm_phase_once(LAS unsigned char* lds, const PT& S, const Epi& E, bool epi_on) {
;     ...
;         const bool has_next = S.next(ui + 1, nxt);
;         const char* nA = has_next ? S.pa(nxt) : cA; const char* nB = has_next ? S.pb(nxt) : cB;
;         for (int t = 0; t < nt; t += 2) {
;             const bool last = (t == nt - 2);
;             const char* a1 = cA + (size_t)(t + 1) * kstep;
;             const char* a2 = last ? nA : cA + (size_t)(t + 2) * kstep; const char* b2 = last ? nB : cB + (size_t)(t + 2) * kstep;
;             const char* a3 = a2 + kstep; const char* b3 = b2 + kstep;
.LBB0_3749:
	s_ashr_i32 s13, s12, 31
	v_cmp_lt_i64_e32 vcc, s[14:15], v[144:145]
	s_lshl_b64 s[14:15], s[12:13], 21
	s_add_u32 s14, s78, s14
	s_addc_u32 s15, s79, s15
	s_and_b64 s[16:17], vcc, exec
	s_cselect_b32 s13, s15, s19
	s_cselect_b32 s39, s14, s18
	s_ashr_i32 s9, s8, 31
	s_lshl_b64 s[16:17], s[8:9], 21
	s_add_u32 s16, s92, s16
	s_addc_u32 s17, s93, s17
	s_and_b64 s[22:23], vcc, exec
	s_cselect_b32 s9, s17, s21
	s_cselect_b32 s40, s16, s20
	s_add_u32 s18, s18, 0x100080
	s_addc_u32 s19, s19, 0
	s_add_u32 s41, s20, 0x100
	s_addc_u32 s42, s21, 0
	s_mov_b32 s43, -2
	s_waitcnt lgkmcnt(0)

;     __device__ __forceinline__ bool next(int i, Unit& u) const {
;         const int nwg = nM * nN; const long L = (long)i * G + c; if (L >= nwg) return false;
;         int wgid = (int)L; { const int q = nwg / NXCD, r = nwg % NXCD, xcd = wgid % NXCD, off = wgid / NXCD; wgid = (xcd < r ? xcd * (q + 1) : r * (q + 1) + (xcd - r) * q) + off; }
;         const int nig = WGM * nN, gid = wgid / nig, fm = gid * WGM, gsz = (nM - fm) < WGM ? (nM - fm) : WGM;
;         u.pm = fm + ((wgid % nig) % gsz); u.pn = (wgid % nig) / gsz; return true;
; template <class PT, class Epi>
; __device__ __forceinline__ void gemm_phase_once(LAS unsigned char* lds, const PT& S, const Epi& E, bool epi_on) {
;     ...
; #pragma unroll
;         for (int a = 0; a < 2; ++a)
; #pragma unroll
;             for (int b = 0; b < 2; ++b)
; #pragma unroll
;                 for (int m = 0; m < 4; ++m)
; #pragma unroll
;                     for (int n = 0; n < 2; ++n) acc[a][b][m][n] = (f32x4){0.f, 0.f, 0.f, 0.f};
.LBB0_3877:
	s_add_i32 s30, s30, 1
	s_mul_i32 s0, s30, s35
	s_mul_hi_u32 s1, s30, s33
	v_mov_b32_e32 v4, 0
	v_mov_b32_e32 v5, 0
	v_mov_b32_e32 v6, 0
	v_mov_b32_e32 v7, 0
	s_nop 1
	v_mfma_f32_16x16x32_bf16 v[8:11], v[4:7], v[4:7], 0
	v_mfma_f32_16x16x32_bf16 v[12:15], v[4:7], v[4:7], 0
	v_mfma_f32_16x16x32_bf16 v[16:19], v[4:7], v[4:7], 0
	v_mfma_f32_32x32x16_bf16 v[20:35], v[4:7], v[4:7], 0
	v_mfma_f32_32x32x16_bf16 v[36:51], v[4:7], v[4:7], 0
	v_mfma_f32_32x32x16_bf16 v[52:67], v[4:7], v[4:7], 0
	v_mfma_f32_32x32x16_bf16 v[68:83], v[4:7], v[4:7], 0
	v_mfma_f32_32x32x16_bf16 v[84:99], v[4:7], v[4:7], 0
	v_mfma_f32_32x32x16_bf16 v[100:115], v[4:7], v[4:7], 0
	v_mfma_f32_32x32x16_bf16 v[116:131], v[4:7], v[4:7], 0
	s_add_i32 s1, s1, s0
	s_mul_i32 s0, s30, s33
	v_readlane_b32 s9, v254, 9
	s_add_u32 s12, s0, s9
	s_addc_u32 s13, s1, s25
	v_cmp_gt_i64_e64 s[0:1], s[12:13], v[146:147]
	s_and_b64 vcc, exec, s[0:1]
	s_cbranch_vccnz .LBB0_3883
	s_ashr_i32 s8, s12, 31
	s_lshr_b32 s8, s8, 29
	s_add_i32 s10, s12, s8
	s_and_b32 s8, s10, -8
	s_sub_i32 s11, s12, s8
	s_cmp_gt_i32 s11, -1
	s_mov_b64 s[8:9], -1
	s_cbranch_scc0 .LBB0_3880
	s_lshl_b32 s14, s11, 4
	s_mov_b64 s[8:9], 0

;     __device__ __forceinline__ const char* pa(const Unit& u) const { return (const char*)(A + (size_t)u.pm * a_tile_stride + (size_t)u.pn * 512); }
;     __device__ __forceinline__ const char* pa(const Unit& u) const { return (const char*)(A + (size_t)u.pm * a_tile_stride + (size_t)((u.pn >> a_group_shift) * a_group_cols)); }
;     __device__ __forceinline__ const char* pb(const Unit& u) const { return (const char*)(Bt + (size_t)u.pn * b_tile_stride); }
; template <class PT, class Epi>
; __device__ __forceinline__ void gemm_phase_once(LAS unsigned char* lds, const PT& S, const Epi& E, bool epi_on) {
;     ...
;         const bool has_next = S.next(ui + 1, nxt);
;         const char* nA = has_next ? S.pa(nxt) : cA; const char* nB = has_next ? S.pb(nxt) : cB;
;         for (int t = 0; t < nt; t += 2) {
;             const bool last = (t == nt - 2);
;             const char* a1 = cA + (size_t)(t + 1) * kstep;
;             const char* a2 = last ? nA : cA + (size_t)(t + 2) * kstep; const char* b2 = last ? nB : cB + (size_t)(t + 2) * kstep;
;             const char* a3 = a2 + kstep; const char* b3 = b2 + kstep;
.LBB0_3883:
	s_ashr_i32 s11, s10, 31
	v_cmp_lt_i64_e32 vcc, s[12:13], v[144:145]
	s_lshl_b64 s[12:13], s[10:11], 20
	s_add_u32 s12, s72, s12
	s_addc_u32 s13, s73, s13
	s_and_b64 s[14:15], vcc, exec
	s_cselect_b32 s11, s13, s19
	s_cselect_b32 s39, s12, s18
	s_ashr_i32 s9, s8, 31
	s_lshl_b64 s[14:15], s[8:9], 20
	s_add_u32 s14, s84, s14
	s_addc_u32 s15, s85, s15
	s_and_b64 s[22:23], vcc, exec
	s_cselect_b32 s9, s15, s21
	s_cselect_b32 s40, s14, s20
	s_add_u32 s18, s18, 0x80080
	s_addc_u32 s19, s19, 0
	s_add_u32 s41, s20, 0x100
	s_addc_u32 s42, s21, 0
	s_mov_b32 s43, -2
	s_waitcnt lgkmcnt(0)
	s_waitcnt vmcnt(0)

;     __device__ __forceinline__ bool next(int i, Unit& u) const {
;         const int nwg = nM * nN; const long L = (long)i * G + c; if (L >= nwg) return false;
;         int wgid = (int)L; { const int q = nwg / NXCD, r = nwg % NXCD, xcd = wgid % NXCD, off = wgid / NXCD; wgid = (xcd < r ? xcd * (q + 1) : r * (q + 1) + (xcd - r) * q) + off; }
;         const int nig = WGM * nN, gid = wgid / nig, fm = gid * WGM, gsz = (nM - fm) < WGM ? (nM - fm) : WGM;
;         u.pm = fm + ((wgid % nig) % gsz); u.pn = (wgid % nig) / gsz; return true;
; template <class PT, class Epi>
; __device__ __forceinline__ void gemm_phase_once(LAS unsigned char* lds, const PT& S, const Epi& E, bool epi_on) {
;     ...
; #pragma unroll
;         for (int a = 0; a < 2; ++a)
; #pragma unroll
;             for (int b = 0; b < 2; ++b)
; #pragma unroll
;                 for (int m = 0; m < 4; ++m)
; #pragma unroll
;                     for (int n = 0; n < 2; ++n) acc[a][b][m][n] = (f32x4){0.f, 0.f, 0.f, 0.f};
.LBB0_3900:
	s_add_i32 s35, s35, 1
	s_mul_i32 s1, s35, s39
	s_mul_hi_u32 s8, s35, s33
	v_mov_b32_e32 v4, 0
	v_mov_b32_e32 v5, 0
	v_mov_b32_e32 v6, 0
	v_mov_b32_e32 v7, 0
	s_nop 1
	v_mfma_f32_16x16x32_bf16 v[8:11], v[4:7], v[4:7], 0
	v_mfma_f32_16x16x32_bf16 v[12:15], v[4:7], v[4:7], 0
	v_mfma_f32_16x16x32_bf16 v[16:19], v[4:7], v[4:7], 0
	v_mfma_f32_32x32x16_bf16 v[20:35], v[4:7], v[4:7], 0
	v_mfma_f32_32x32x16_bf16 v[36:51], v[4:7], v[4:7], 0
	v_mfma_f32_32x32x16_bf16 v[52:67], v[4:7], v[4:7], 0
	v_mfma_f32_32x32x16_bf16 v[68:83], v[4:7], v[4:7], 0
	v_mfma_f32_32x32x16_bf16 v[84:99], v[4:7], v[4:7], 0
	v_mfma_f32_32x32x16_bf16 v[100:115], v[4:7], v[4:7], 0
	v_mfma_f32_32x32x16_bf16 v[116:131], v[4:7], v[4:7], 0
	s_add_i32 s8, s8, s1
	s_mul_i32 s1, s35, s33
	s_add_u32 s14, s1, s26
	s_addc_u32 s15, s8, s40
	v_cmp_gt_i64_e64 s[8:9], s[14:15], 15
	s_and_b64 vcc, exec, s[8:9]
	s_cbranch_vccnz .LBB0_3906
	s_ashr_i32 s1, s14, 31
	s_lshr_b32 s1, s1, 29
	s_add_i32 s1, s14, s1
	s_and_b32 s10, s1, -8
	s_sub_i32 s12, s14, s10
	s_cmp_gt_i32 s12, -1
	s_mov_b64 s[10:11], -1
	s_cbranch_scc0 .LBB0_3903
	s_lshl_b32 s13, s12, 1
	s_mov_b64 s[10:11], 0

;     __device__ __forceinline__ const char* pa(const Unit& u) const { return (const char*)(A + (size_t)u.pm * a_tile_stride + (size_t)u.pn * 512); }
;     __device__ __forceinline__ bool next(int i, Unit& u) const {
;     ...
;         const int nig = WGM * nN, gid = wgid / nig, fm = gid * WGM, gsz = (nM - fm) < WGM ? (nM - fm) : WGM;
;         u.pm = fm + ((wgid % nig) % gsz); u.pn = (wgid % nig) / gsz; return true;
;     }
;     __device__ __forceinline__ const char* pa(const Unit& u) const { return (const char*)(A + (size_t)u.pm * a_tile_stride + (size_t)((u.pn >> a_group_shift) * a_group_cols)); }
;     __device__ __forceinline__ const char* pb(const Unit& u) const { return (const char*)(Bt + (size_t)u.pn * b_tile_stride); }
; template <class PT, class Epi>
; __device__ __forceinline__ void gemm_phase_once(LAS unsigned char* lds, const PT& S, const Epi& E, bool epi_on) {
;     ...
;         const bool has_next = S.next(ui + 1, nxt);
;         const char* nA = has_next ? S.pa(nxt) : cA; const char* nB = has_next ? S.pb(nxt) : cB;
;         for (int t = 0; t < nt; t += 2) {
;             const bool last = (t == nt - 2);
;             const char* a1 = cA + (size_t)(t + 1) * kstep;
;             const char* a2 = last ? nA : cA + (size_t)(t + 2) * kstep; const char* b2 = last ? nB : cB + (size_t)(t + 2) * kstep;
;             const char* a3 = a2 + kstep; const char* b3 = b2 + kstep;
.LBB0_3905:
	s_ashr_i32 s1, s1, 3
	s_add_i32 s1, s13, s1
	s_ashr_i32 s10, s1, 31
	s_lshr_b32 s10, s10, 27
	s_add_i32 s10, s1, s10
	s_ashr_i32 s11, s10, 5
	s_lshl_b32 s11, s11, 3
	s_sub_i32 s12, 4, s11
	s_min_i32 s12, s12, 8
	s_abs_i32 s13, s12
	v_cvt_f32_u32_e32 v140, s13
	s_sub_i32 s17, 0, s13
	s_andn2_b32 s10, s10, 31
	s_sub_i32 s1, s1, s10
	v_rcp_iflag_f32_e32 v140, v140
	s_abs_i32 s10, s1
	s_xor_b32 s16, s1, s12
	s_ashr_i32 s16, s16, 31
	v_mul_f32_e32 v140, 0x4f7ffffe, v140
	v_cvt_u32_f32_e32 v140, v140
	s_nop 0
	v_readfirstlane_b32 s19, v140
	s_mul_i32 s17, s17, s19
	s_mul_hi_u32 s17, s19, s17
	s_add_i32 s19, s19, s17
	s_mul_hi_u32 s17, s10, s19
	s_mul_i32 s19, s17, s13
	s_sub_i32 s10, s10, s19
	s_add_i32 s24, s17, 1
	s_sub_i32 s19, s10, s13
	s_cmp_ge_u32 s10, s13
	s_cselect_b32 s17, s24, s17
	s_cselect_b32 s10, s19, s10
	s_add_i32 s19, s17, 1
	s_cmp_ge_u32 s10, s13
	s_cselect_b32 s10, s19, s17
	s_xor_b32 s10, s10, s16
	s_sub_i32 s10, s10, s16
	s_mul_i32 s12, s10, s12
	s_sub_i32 s1, s1, s12
	s_add_i32 s12, s11, s1
.LBB0_3906:
	s_ashr_i32 s13, s12, 31
	v_cmp_lt_i64_e64 s[24:25], s[14:15], 16
	s_lshl_b64 s[14:15], s[12:13], 20
	s_add_u32 s14, s81, s14
	s_addc_u32 s15, s96, s15
	s_and_b64 s[16:17], s[24:25], exec
	s_cselect_b32 s1, s15, s21
	s_cselect_b32 s13, s14, s20
	s_ashr_i32 s11, s10, 31
	s_lshl_b64 s[16:17], s[10:11], 20
	s_add_u32 s16, s82, s16
	s_addc_u32 s17, s83, s17
	s_and_b64 s[24:25], s[24:25], exec
	s_cselect_b32 s11, s17, s23
	s_cselect_b32 s19, s16, s22
	s_add_u32 s20, s20, 0x80080
	s_addc_u32 s21, s21, 0
	s_add_u32 s45, s22, 0x100
	s_addc_u32 s46, s23, 0
	s_mov_b32 s47, -2
	s_waitcnt lgkmcnt(0)

;     __device__ __forceinline__ const char* pa(const Unit& u) const { return (const char*)(A + (size_t)u.pm * a_tile_stride + (size_t)u.pn * 512); }
;     __device__ __forceinline__ const char* pa(const Unit& u) const { return (const char*)(A + (size_t)u.pm * a_tile_stride + (size_t)((u.pn >> a_group_shift) * a_group_cols)); }
;     __device__ __forceinline__ const char* pb(const Unit& u) const { return (const char*)(Bt + (size_t)u.pn * b_tile_stride); }
; template <class PT, class Epi>
; __device__ __forceinline__ void gemm_phase_once(LAS unsigned char* lds, const PT& S, const Epi& E, bool epi_on) {
;     ...
;         const bool has_next = S.next(ui + 1, nxt);
;         const char* nA = has_next ? S.pa(nxt) : cA; const char* nB = has_next ? S.pb(nxt) : cB;
;         for (int t = 0; t < nt; t += 2) {
;             const bool last = (t == nt - 2);
;             const char* a1 = cA + (size_t)(t + 1) * kstep;
;             const char* a2 = last ? nA : cA + (size_t)(t + 2) * kstep; const char* b2 = last ? nB : cB + (size_t)(t + 2) * kstep;
;             const char* a3 = a2 + kstep; const char* b3 = b2 + kstep;
.LBB0_4222:
	s_ashr_i32 s13, s12, 31
	v_cmp_lt_i64_e32 vcc, s[14:15], v[144:145]
	s_lshl_b64 s[14:15], s[12:13], 18
	v_readlane_b32 s16, v254, 48
	v_readlane_b32 s17, v254, 49
	s_add_u32 s14, s16, s14
	s_addc_u32 s15, s17, s15
	s_and_b64 s[16:17], vcc, exec
	s_cselect_b32 s13, s15, s19
	s_cselect_b32 s39, s14, s18
	s_ashr_i32 s9, s8, 31
	s_lshl_b64 s[16:17], s[8:9], 18
	v_readlane_b32 s22, v254, 7
	v_readlane_b32 s23, v254, 8
	s_add_u32 s16, s22, s16
	s_addc_u32 s17, s23, s17
	s_and_b64 s[22:23], vcc, exec
	s_cselect_b32 s9, s17, s21
	s_cselect_b32 s40, s16, s20
	s_add_u32 s18, s18, 0x20080
	s_addc_u32 s19, s19, 0
	s_add_u32 s41, s20, 0x100
	s_addc_u32 s42, s21, 0
	s_mov_b32 s43, -2
	s_waitcnt lgkmcnt(0)

;     __device__ __forceinline__ const char* pa(const Unit& u) const { return (const char*)(A + (size_t)u.pm * a_tile_stride + (size_t)u.pn * 512); }
;     __device__ __forceinline__ bool next(int i, Unit& u) const {
;         const int nwg = nM * nN; const long L = (long)i * G + c; if (L >= nwg) return false;
;         int wgid = (int)L; { const int q = nwg / NXCD, r = nwg % NXCD, xcd = wgid % NXCD, off = wgid / NXCD; wgid = (xcd < r ? xcd * (q + 1) : r * (q + 1) + (xcd - r) * q) + off; }
;         const int nig = WGM * nN, gid = wgid / nig, fm = gid * WGM, gsz = (nM - fm) < WGM ? (nM - fm) : WGM;
;         u.pm = fm + ((wgid % nig) % gsz); u.pn = (wgid % nig) / gsz; return true;
;     }
;     __device__ __forceinline__ const char* pa(const Unit& u) const { return (const char*)(A + (size_t)u.pm * a_tile_stride + (size_t)((u.pn >> a_group_shift) * a_group_cols)); }
;     __device__ __forceinline__ const char* pb(const Unit& u) const { return (const char*)(Bt + (size_t)u.pn * b_tile_stride); }
; template <class PT, class Epi>
; __device__ __forceinline__ void gemm_phase_once(LAS unsigned char* lds, const PT& S, const Epi& E, bool epi_on) {
;     ...
; #pragma unroll
;         for (int a = 0; a < 2; ++a)
; #pragma unroll
;             for (int b = 0; b < 2; ++b)
; #pragma unroll
;                 for (int m = 0; m < 4; ++m)
; #pragma unroll
;                     for (int n = 0; n < 2; ++n) acc[a][b][m][n] = (f32x4){0.f, 0.f, 0.f, 0.f};
.LBB0_4347:
	s_add_i32 s53, s53, 1
	s_mul_i32 s0, s53, s56
	s_mul_hi_u32 s1, s53, s33
	v_mov_b32_e32 v4, 0
	v_mov_b32_e32 v5, 0
	v_mov_b32_e32 v6, 0
	v_mov_b32_e32 v7, 0
	s_nop 1
	v_mfma_f32_16x16x32_bf16 v[8:11], v[4:7], v[4:7], 0
	v_mfma_f32_16x16x32_bf16 v[12:15], v[4:7], v[4:7], 0
	v_mfma_f32_16x16x32_bf16 v[16:19], v[4:7], v[4:7], 0
	v_mfma_f32_32x32x16_bf16 v[20:35], v[4:7], v[4:7], 0
	v_mfma_f32_32x32x16_bf16 v[44:59], v[4:7], v[4:7], 0
	v_mfma_f32_32x32x16_bf16 v[60:75], v[4:7], v[4:7], 0
	v_mfma_f32_32x32x16_bf16 v[76:91], v[4:7], v[4:7], 0
	v_mfma_f32_32x32x16_bf16 v[92:107], v[4:7], v[4:7], 0
	v_mfma_f32_32x32x16_bf16 v[108:123], v[4:7], v[4:7], 0
	v_mfma_f32_32x32x16_bf16 v[124:139], v[4:7], v[4:7], 0
	s_add_i32 s1, s1, s0
	s_mul_i32 s0, s53, s33
	v_readlane_b32 s25, v254, 9
	s_add_u32 s28, s0, s25
	s_addc_u32 s29, s1, s47
	v_cmp_gt_i64_e64 s[0:1], s[28:29], v[156:157]
	s_and_b64 vcc, exec, s[0:1]
	s_cbranch_vccnz .LBB0_4349
	s_ashr_i32 s24, s28, 31
	s_lshr_b32 s24, s24, 29
	s_add_i32 s24, s28, s24
	s_ashr_i32 s25, s24, 3
	s_and_b32 s24, s24, -8
	s_sub_i32 s24, s28, s24
	s_cmp_lt_i32 s24, 0
	s_cselect_b32 s26, s48, 0x160
	s_mul_i32 s24, s26, s24
	s_add_i32 s24, s24, s25
	s_mul_hi_i32 s25, s24, 0x2e8ba2e9
	s_lshr_b32 s26, s25, 31
	s_ashr_i32 s25, s25, 6
	s_add_i32 s25, s25, s26
	s_lshl_b32 s26, s25, 3
	s_sub_i32 s27, 64, s26
	s_min_i32 s27, s27, 8
	s_abs_i32 s30, s27
	v_cvt_f32_u32_e32 v40, s30
	s_sub_i32 s35, 0, s30
	s_mulk_i32 s25, 0x160
	s_sub_i32 s25, s24, s25
	v_rcp_iflag_f32_e32 v40, v40
	s_abs_i32 s24, s25
	s_xor_b32 s31, s25, s27
	s_ashr_i32 s31, s31, 31
	v_mul_f32_e32 v40, 0x4f7ffffe, v40
	v_cvt_u32_f32_e32 v40, v40
	s_nop 0
	v_readfirstlane_b32 s40, v40
	s_mul_i32 s35, s35, s40
	s_mul_hi_u32 s35, s40, s35
	s_add_i32 s40, s40, s35
	s_mul_hi_u32 s35, s24, s40
	s_mul_i32 s40, s35, s30
	s_sub_i32 s24, s24, s40
	s_add_i32 s41, s35, 1
	s_sub_i32 s40, s24, s30
	s_cmp_ge_u32 s24, s30
	s_cselect_b32 s35, s41, s35
	s_cselect_b32 s24, s40, s24
	s_add_i32 s40, s35, 1
	s_cmp_ge_u32 s24, s30
	s_cselect_b32 s24, s40, s35
	s_xor_b32 s24, s24, s31
	s_sub_i32 s24, s24, s31
	s_mul_i32 s27, s24, s27
	s_sub_i32 s25, s25, s27
	s_add_i32 s26, s25, s26
.LBB0_4349:
	s_ashr_i32 s27, s26, 31
	v_cmp_lt_i64_e32 vcc, s[28:29], v[154:155]
	s_lshl_b64 s[28:29], s[26:27], 20
	s_add_u32 s28, s72, s28
	s_addc_u32 s29, s73, s29
	s_and_b64 s[30:31], vcc, exec
	s_cselect_b32 s27, s29, s37
	s_cselect_b32 s35, s28, s36
	s_ashr_i32 s25, s24, 31
	s_lshl_b64 s[30:31], s[24:25], 20
	s_add_u32 s30, s76, s30
	s_addc_u32 s31, s77, s31
	s_and_b64 s[40:41], vcc, exec
	s_cselect_b32 s25, s31, s39
	s_cselect_b32 s62, s30, s38
	s_add_u32 s63, s38, 0x100
	s_addc_u32 s64, s39, 0
	s_mov_b32 s65, -2
	s_waitcnt lgkmcnt(0)
	s_waitcnt vmcnt(0)

;     __device__ __forceinline__ const char* pa(const Unit& u) const { return (const char*)(A + (size_t)u.pm * a_tile_stride + (size_t)((u.pn >> a_group_shift) * a_group_cols)); }
;     __device__ __forceinline__ const char* pb(const Unit& u) const { return (const char*)(Bt + (size_t)u.pn * b_tile_stride); }
;     __device__ __forceinline__ const char* pa(const Unit& u) const { return (const char*)(A + (size_t)u.pm * a_tile_stride + (size_t)u.pn * 512); }
; template <class PT, class Epi>
; __device__ __forceinline__ void gemm_phase_once(LAS unsigned char* lds, const PT& S, const Epi& E, bool epi_on) {
;     ...
;         const bool has_next = S.next(ui + 1, nxt);
;         const char* nA = has_next ? S.pa(nxt) : cA; const char* nB = has_next ? S.pb(nxt) : cB;
;         for (int t = 0; t < nt; t += 2) {
;             const bool last = (t == nt - 2);
;             const char* a1 = cA + (size_t)(t + 1) * kstep;
;             const char* a2 = last ? nA : cA + (size_t)(t + 2) * kstep; const char* b2 = last ? nB : cB + (size_t)(t + 2) * kstep;
;             const char* a3 = a2 + kstep; const char* b3 = b2 + kstep;
;     ...
; #pragma unroll
;         for (int a = 0; a < 2; ++a)
; #pragma unroll
;             for (int b = 0; b < 2; ++b)
; #pragma unroll
;                 for (int m = 0; m < 4; ++m)
; #pragma unroll
;                     for (int n = 0; n < 2; ++n) acc[a][b][m][n] = (f32x4){0.f, 0.f, 0.f, 0.f};
.LBB0_4817:
	s_xor_b64 s[0:1], s[14:15], -1
	s_mov_b64 s[18:19], s[6:7]
	s_and_b64 s[6:7], s[14:15], exec
	v_mov_b32_e32 v4, 0
	v_mov_b32_e32 v5, 0
	v_mov_b32_e32 v6, 0
	v_mov_b32_e32 v7, 0
	s_nop 1
	v_mfma_f32_16x16x32_bf16 v[8:11], v[4:7], v[4:7], 0
	v_mfma_f32_16x16x32_bf16 v[12:15], v[4:7], v[4:7], 0
	v_mfma_f32_16x16x32_bf16 v[16:19], v[4:7], v[4:7], 0
	v_mfma_f32_32x32x16_bf16 v[20:35], v[4:7], v[4:7], 0
	v_mfma_f32_32x32x16_bf16 v[36:51], v[4:7], v[4:7], 0
	v_mfma_f32_32x32x16_bf16 v[52:67], v[4:7], v[4:7], 0
	v_mfma_f32_32x32x16_bf16 v[68:83], v[4:7], v[4:7], 0
	v_mfma_f32_32x32x16_bf16 v[84:99], v[4:7], v[4:7], 0
	v_mfma_f32_32x32x16_bf16 v[100:115], v[4:7], v[4:7], 0
	v_mfma_f32_32x32x16_bf16 v[116:131], v[4:7], v[4:7], 0
	s_mov_b64 s[16:17], s[8:9]
	s_cselect_b32 s8, s28, s28
	s_cselect_b32 s6, s29, s29
	s_ashr_i32 s9, s8, 31
	s_lshl_b64 s[8:9], s[8:9], 20
	s_add_u32 s8, s72, s8
	s_addc_u32 s9, s73, s9
	s_and_b64 s[36:37], s[14:15], exec
	s_cselect_b32 s13, s9, s17
	s_cselect_b32 s35, s8, s16
	s_ashr_i32 s7, s6, 31
	s_lshl_b64 s[6:7], s[6:7], 20
	v_readlane_b32 s36, v254, 5
	v_readlane_b32 s37, v254, 6
	s_add_u32 s6, s36, s6
	s_addc_u32 s7, s37, s7
	s_and_b64 s[14:15], s[14:15], exec
	s_cselect_b32 s36, s7, s19
	s_cselect_b32 s37, s6, s18
	s_add_u32 s14, s16, 0x80080
	s_addc_u32 s15, s17, 0
	s_add_u32 s38, s18, 0x100
	s_addc_u32 s39, s19, 0
	s_mov_b32 s40, -2
	s_waitcnt lgkmcnt(0)
	s_waitcnt vmcnt(0)

;     __device__ __forceinline__ bool next(int i, Unit& u) const {
;         const int nwg = nM * nN; const long L = (long)i * G + c; if (L >= nwg) return false;
;         int wgid = (int)L; { const int q = nwg / NXCD, r = nwg % NXCD, xcd = wgid % NXCD, off = wgid / NXCD; wgid = (xcd < r ? xcd * (q + 1) : r * (q + 1) + (xcd - r) * q) + off; }
;         const int nig = WGM * nN, gid = wgid / nig, fm = gid * WGM, gsz = (nM - fm) < WGM ? (nM - fm) : WGM;
;         u.pm = fm + ((wgid % nig) % gsz); u.pn = (wgid % nig) / gsz; return true;
; template <class PT, class Epi>
; __device__ __forceinline__ void gemm_phase_once(LAS unsigned char* lds, const PT& S, const Epi& E, bool epi_on) {
;     ...
; #pragma unroll
;         for (int a = 0; a < 2; ++a)
; #pragma unroll
;             for (int b = 0; b < 2; ++b)
; #pragma unroll
;                 for (int m = 0; m < 4; ++m)
; #pragma unroll
;                     for (int n = 0; n < 2; ++n) acc[a][b][m][n] = (f32x4){0.f, 0.f, 0.f, 0.f};
.LBB0_5011:
	s_add_i32 s34, s34, 1
	s_mul_i32 s0, s34, s37
	s_mul_hi_u32 s1, s34, s33
	v_mov_b32_e32 v4, 0
	v_mov_b32_e32 v5, 0
	v_mov_b32_e32 v6, 0
	v_mov_b32_e32 v7, 0
	s_nop 1
	v_mfma_f32_16x16x32_bf16 v[8:11], v[4:7], v[4:7], 0
	v_mfma_f32_16x16x32_bf16 v[12:15], v[4:7], v[4:7], 0
	v_mfma_f32_16x16x32_bf16 v[16:19], v[4:7], v[4:7], 0
	v_mfma_f32_32x32x16_bf16 v[20:35], v[4:7], v[4:7], 0
	v_mfma_f32_32x32x16_bf16 v[36:51], v[4:7], v[4:7], 0
	v_mfma_f32_32x32x16_bf16 v[52:67], v[4:7], v[4:7], 0
	v_mfma_f32_32x32x16_bf16 v[76:91], v[4:7], v[4:7], 0
	v_mfma_f32_32x32x16_bf16 v[92:107], v[4:7], v[4:7], 0
	v_mfma_f32_32x32x16_bf16 v[108:123], v[4:7], v[4:7], 0
	v_mfma_f32_32x32x16_bf16 v[124:139], v[4:7], v[4:7], 0
	s_add_i32 s1, s1, s0
	s_mul_i32 s0, s34, s33
	v_readlane_b32 s11, v254, 9
	s_add_u32 s14, s0, s11
	s_addc_u32 s15, s1, s27
	v_cmp_gt_i64_e64 s[0:1], s[14:15], v[154:155]
	s_and_b64 vcc, exec, s[0:1]
	s_cbranch_vccnz .LBB0_5017
	s_ashr_i32 s10, s14, 31
	s_lshr_b32 s10, s10, 29
	s_add_i32 s12, s14, s10
	s_and_b32 s10, s12, -8
	s_sub_i32 s13, s14, s10
	s_cmp_gt_i32 s13, -1
	s_mov_b64 s[10:11], -1
	s_cbranch_scc0 .LBB0_5014
	s_lshl_b32 s16, s13, 6
	s_mov_b64 s[10:11], 0

;     __device__ __forceinline__ const char* pa(const Unit& u) const { return (const char*)(A + (size_t)u.pm * a_tile_stride + (size_t)u.pn * 512); }
;     __device__ __forceinline__ bool next(int i, Unit& u) const {
;     ...
;         int wgid = (int)L; { const int q = nwg / NXCD, r = nwg % NXCD, xcd = wgid % NXCD, off = wgid / NXCD; wgid = (xcd < r ? xcd * (q + 1) : r * (q + 1) + (xcd - r) * q) + off; }
;         const int nig = WGM * nN, gid = wgid / nig, fm = gid * WGM, gsz = (nM - fm) < WGM ? (nM - fm) : WGM;
;         u.pm = fm + ((wgid % nig) % gsz); u.pn = (wgid % nig) / gsz; return true;
;     }
;     __device__ __forceinline__ const char* pa(const Unit& u) const { return (const char*)(A + (size_t)u.pm * a_tile_stride + (size_t)((u.pn >> a_group_shift) * a_group_cols)); }
;     __device__ __forceinline__ const char* pb(const Unit& u) const { return (const char*)(Bt + (size_t)u.pn * b_tile_stride); }
; template <class PT, class Epi>
; __device__ __forceinline__ void gemm_phase_once(LAS unsigned char* lds, const PT& S, const Epi& E, bool epi_on) {
;     ...
;         const bool has_next = S.next(ui + 1, nxt);
;         const char* nA = has_next ? S.pa(nxt) : cA; const char* nB = has_next ? S.pb(nxt) : cB;
;         for (int t = 0; t < nt; t += 2) {
;             const bool last = (t == nt - 2);
;             const char* a1 = cA + (size_t)(t + 1) * kstep;
;             const char* a2 = last ? nA : cA + (size_t)(t + 2) * kstep; const char* b2 = last ? nB : cB + (size_t)(t + 2) * kstep;
;             const char* a3 = a2 + kstep; const char* b3 = b2 + kstep;
.LBB0_5016:
	s_ashr_i32 s10, s12, 3
	s_add_i32 s10, s16, s10
	s_ashr_i32 s11, s10, 31
	s_lshr_b32 s11, s11, 26
	s_add_i32 s11, s10, s11
	s_ashr_i32 s12, s11, 6
	s_lshl_b32 s12, s12, 3
	s_sub_i32 s13, 64, s12
	s_min_i32 s13, s13, 8
	s_abs_i32 s16, s13
	v_cvt_f32_u32_e32 v72, s16
	s_sub_i32 s24, 0, s16
	s_andn2_b32 s11, s11, 63
	s_sub_i32 s11, s10, s11
	v_rcp_iflag_f32_e32 v72, v72
	s_abs_i32 s10, s11
	s_xor_b32 s17, s11, s13
	s_ashr_i32 s17, s17, 31
	v_mul_f32_e32 v72, 0x4f7ffffe, v72
	v_cvt_u32_f32_e32 v72, v72
	s_nop 0
	v_readfirstlane_b32 s25, v72
	s_mul_i32 s24, s24, s25
	s_mul_hi_u32 s24, s25, s24
	s_add_i32 s25, s25, s24
	s_mul_hi_u32 s24, s10, s25
	s_mul_i32 s25, s24, s16
	s_sub_i32 s10, s10, s25
	s_add_i32 s41, s24, 1
	s_sub_i32 s25, s10, s16
	s_cmp_ge_u32 s10, s16
	s_cselect_b32 s24, s41, s24
	s_cselect_b32 s10, s25, s10
	s_add_i32 s25, s24, 1
	s_cmp_ge_u32 s10, s16
	s_cselect_b32 s10, s25, s24
	s_xor_b32 s10, s10, s17
	s_sub_i32 s10, s10, s17
	s_mul_i32 s13, s10, s13
	s_sub_i32 s11, s11, s13
	s_add_i32 s12, s12, s11
.LBB0_5017:
	s_ashr_i32 s13, s12, 31
	v_cmp_lt_i64_e32 vcc, s[14:15], v[152:153]
	s_lshl_b64 s[14:15], s[12:13], 20
	s_add_u32 s11, s2, s14
	s_addc_u32 s13, s3, s15
	s_lshl_b32 s14, s10, 8
	s_and_b32 s14, s14, 0xfffffe00
	s_ashr_i32 s15, s14, 31
	s_lshl_b64 s[14:15], s[14:15], 1
	s_add_u32 s14, s11, s14
	s_addc_u32 s15, s13, s15
	s_and_b64 s[16:17], vcc, exec
	s_cselect_b32 s13, s15, s21
	s_cselect_b32 s41, s14, s20
	s_ashr_i32 s11, s10, 31
	s_lshl_b64 s[16:17], s[10:11], 18
	v_readlane_b32 s24, v254, 52
	v_readlane_b32 s25, v254, 53
	s_add_u32 s16, s24, s16
	s_addc_u32 s17, s25, s17
	s_and_b64 s[24:25], vcc, exec
	s_cselect_b32 s11, s17, s23
	s_cselect_b32 s42, s16, s22
	s_add_u32 s20, s20, 0x80080
	s_addc_u32 s21, s21, 0
	s_add_u32 s43, s22, 0x100
	s_addc_u32 s44, s23, 0
	s_mov_b32 s45, -2
	s_waitcnt lgkmcnt(0)
	s_waitcnt vmcnt(0)

;     __device__ __forceinline__ bool next(int i, Unit& u) const {
;         const int nwg = nM * nN; const long L = (long)i * G + c; if (L >= nwg) return false;
;         int wgid = (int)L; { const int q = nwg / NXCD, r = nwg % NXCD, xcd = wgid % NXCD, off = wgid / NXCD; wgid = (xcd < r ? xcd * (q + 1) : r * (q + 1) + (xcd - r) * q) + off; }
;         const int nig = WGM * nN, gid = wgid / nig, fm = gid * WGM, gsz = (nM - fm) < WGM ? (nM - fm) : WGM;
;         u.pm = fm + ((wgid % nig) % gsz); u.pn = (wgid % nig) / gsz; return true;
; template <class PT, class Epi>
; __device__ __forceinline__ void gemm_phase_once(LAS unsigned char* lds, const PT& S, const Epi& E, bool epi_on) {
;     ...
; #pragma unroll
;         for (int a = 0; a < 2; ++a)
; #pragma unroll
;             for (int b = 0; b < 2; ++b)
; #pragma unroll
;                 for (int m = 0; m < 4; ++m)
; #pragma unroll
;                     for (int n = 0; n < 2; ++n) acc[a][b][m][n] = (f32x4){0.f, 0.f, 0.f, 0.f};
.LBB0_5086:
	s_add_i32 s30, s30, 1
	s_mul_i32 s0, s30, s35
	s_mul_hi_u32 s1, s30, s33
	v_mov_b32_e32 v4, 0
	v_mov_b32_e32 v5, 0
	v_mov_b32_e32 v6, 0
	v_mov_b32_e32 v7, 0
	s_nop 1
	v_mfma_f32_16x16x32_bf16 v[8:11], v[4:7], v[4:7], 0
	v_mfma_f32_16x16x32_bf16 v[12:15], v[4:7], v[4:7], 0
	v_mfma_f32_16x16x32_bf16 v[16:19], v[4:7], v[4:7], 0
	v_mfma_f32_32x32x16_bf16 v[20:35], v[4:7], v[4:7], 0
	v_mfma_f32_32x32x16_bf16 v[36:51], v[4:7], v[4:7], 0
	v_mfma_f32_32x32x16_bf16 v[52:67], v[4:7], v[4:7], 0
	v_mfma_f32_32x32x16_bf16 v[68:83], v[4:7], v[4:7], 0
	v_mfma_f32_32x32x16_bf16 v[84:99], v[4:7], v[4:7], 0
	v_mfma_f32_32x32x16_bf16 v[100:115], v[4:7], v[4:7], 0
	v_mfma_f32_32x32x16_bf16 v[116:131], v[4:7], v[4:7], 0
	s_add_i32 s1, s1, s0
	s_mul_i32 s0, s30, s33
	v_readlane_b32 s9, v254, 9
	s_add_u32 s12, s0, s9
	s_addc_u32 s13, s1, s25
	v_cmp_gt_i64_e64 s[0:1], s[12:13], v[146:147]
	s_and_b64 vcc, exec, s[0:1]
	s_cbranch_vccnz .LBB0_5092
	s_ashr_i32 s8, s12, 31
	s_lshr_b32 s8, s8, 29
	s_add_i32 s10, s12, s8
	s_and_b32 s8, s10, -8
	s_sub_i32 s11, s12, s8
	s_cmp_gt_i32 s11, -1
	s_mov_b64 s[8:9], -1
	s_cbranch_scc0 .LBB0_5089
	s_lshl_b32 s14, s11, 6
	s_mov_b64 s[8:9], 0

;     __device__ __forceinline__ const char* pa(const Unit& u) const { return (const char*)(A + (size_t)u.pm * a_tile_stride + (size_t)u.pn * 512); }
;     __device__ __forceinline__ bool next(int i, Unit& u) const {
;     ...
;         const int nig = WGM * nN, gid = wgid / nig, fm = gid * WGM, gsz = (nM - fm) < WGM ? (nM - fm) : WGM;
;         u.pm = fm + ((wgid % nig) % gsz); u.pn = (wgid % nig) / gsz; return true;
;     }
;     __device__ __forceinline__ const char* pa(const Unit& u) const { return (const char*)(A + (size_t)u.pm * a_tile_stride + (size_t)((u.pn >> a_group_shift) * a_group_cols)); }
;     __device__ __forceinline__ const char* pb(const Unit& u) const { return (const char*)(Bt + (size_t)u.pn * b_tile_stride); }
; template <class PT, class Epi>
; __device__ __forceinline__ void gemm_phase_once(LAS unsigned char* lds, const PT& S, const Epi& E, bool epi_on) {
;     ...
;         const bool has_next = S.next(ui + 1, nxt);
;         const char* nA = has_next ? S.pa(nxt) : cA; const char* nB = has_next ? S.pb(nxt) : cB;
;         for (int t = 0; t < nt; t += 2) {
;             const bool last = (t == nt - 2);
;             const char* a1 = cA + (size_t)(t + 1) * kstep;
;             const char* a2 = last ? nA : cA + (size_t)(t + 2) * kstep; const char* b2 = last ? nB : cB + (size_t)(t + 2) * kstep;
;             const char* a3 = a2 + kstep; const char* b3 = b2 + kstep;
.LBB0_5091:
	s_ashr_i32 s8, s10, 3
	s_add_i32 s8, s14, s8
	s_ashr_i32 s9, s8, 31
	s_lshr_b32 s9, s9, 26
	s_add_i32 s9, s8, s9
	s_ashr_i32 s10, s9, 6
	s_lshl_b32 s10, s10, 3
	s_sub_i32 s11, 64, s10
	s_min_i32 s11, s11, 8
	s_abs_i32 s14, s11
	v_cvt_f32_u32_e32 v153, s14
	s_sub_i32 s22, 0, s14
	s_andn2_b32 s9, s9, 63
	s_sub_i32 s9, s8, s9
	v_rcp_iflag_f32_e32 v153, v153
	s_abs_i32 s8, s9
	s_xor_b32 s15, s9, s11
	s_ashr_i32 s15, s15, 31
	v_mul_f32_e32 v153, 0x4f7ffffe, v153
	v_cvt_u32_f32_e32 v153, v153
	s_nop 0
	v_readfirstlane_b32 s23, v153
	s_mul_i32 s22, s22, s23
	s_mul_hi_u32 s22, s23, s22
	s_add_i32 s23, s23, s22
	s_mul_hi_u32 s22, s8, s23
	s_mul_i32 s23, s22, s14
	s_sub_i32 s8, s8, s23
	s_add_i32 s39, s22, 1
	s_sub_i32 s23, s8, s14
	s_cmp_ge_u32 s8, s14
	s_cselect_b32 s22, s39, s22
	s_cselect_b32 s8, s23, s8
	s_add_i32 s23, s22, 1
	s_cmp_ge_u32 s8, s14
	s_cselect_b32 s8, s23, s22
	s_xor_b32 s8, s8, s15
	s_sub_i32 s8, s8, s15
	s_mul_i32 s11, s8, s11
	s_sub_i32 s9, s9, s11
	s_add_i32 s10, s10, s9
.LBB0_5092:
	s_ashr_i32 s11, s10, 31
	v_cmp_lt_i64_e32 vcc, s[12:13], v[144:145]
	s_lshl_b64 s[12:13], s[10:11], 20
	s_add_u32 s12, s78, s12
	s_addc_u32 s13, s79, s13
	s_and_b64 s[14:15], vcc, exec
	s_cselect_b32 s11, s13, s19
	s_cselect_b32 s39, s12, s18
	s_ashr_i32 s9, s8, 31
	s_lshl_b64 s[14:15], s[8:9], 20
	s_add_u32 s14, s92, s14
	s_addc_u32 s15, s93, s15
	s_and_b64 s[22:23], vcc, exec
	s_cselect_b32 s9, s15, s21
	s_cselect_b32 s40, s14, s20
	s_add_u32 s18, s18, 0x80080
	s_addc_u32 s19, s19, 0
	s_add_u32 s41, s20, 0x100
	s_addc_u32 s42, s21, 0
	s_mov_b32 s43, -2
	s_waitcnt lgkmcnt(0)

;     __device__ __forceinline__ const char* pa(const Unit& u) const { return (const char*)(A + (size_t)u.pm * a_tile_stride + (size_t)u.pn * 512); }
;     __device__ __forceinline__ bool next(int i, Unit& u) const {
;     ...
;         const int nig = WGM * nN, gid = wgid / nig, fm = gid * WGM, gsz = (nM - fm) < WGM ? (nM - fm) : WGM;
;         u.pm = fm + ((wgid % nig) % gsz); u.pn = (wgid % nig) / gsz; return true;
;     }
;     __device__ __forceinline__ const char* pa(const Unit& u) const { return (const char*)(A + (size_t)u.pm * a_tile_stride + (size_t)((u.pn >> a_group_shift) * a_group_cols)); }
;     __device__ __forceinline__ const char* pb(const Unit& u) const { return (const char*)(Bt + (size_t)u.pn * b_tile_stride); }
; template <class PT, class Epi>
; __device__ __forceinline__ void gemm_phase_once(LAS unsigned char* lds, const PT& S, const Epi& E, bool epi_on) {
;     ...
;         const bool has_next = S.next(ui + 1, nxt);
;         const char* nA = has_next ? S.pa(nxt) : cA; const char* nB = has_next ? S.pb(nxt) : cB;
;         for (int t = 0; t < nt; t += 2) {
;             const bool last = (t == nt - 2);
;             const char* a1 = cA + (size_t)(t + 1) * kstep;
;             const char* a2 = last ? nA : cA + (size_t)(t + 2) * kstep; const char* b2 = last ? nB : cB + (size_t)(t + 2) * kstep;
;             const char* a3 = a2 + kstep; const char* b3 = b2 + kstep;
.LBB0_5225:
	s_ashr_i32 s8, s10, 3
	s_add_i32 s8, s14, s8
	s_ashr_i32 s9, s8, 31
	s_lshr_b32 s9, s9, 28
	s_add_i32 s9, s8, s9
	s_ashr_i32 s10, s9, 4
	s_lshl_b32 s10, s10, 3
	s_sub_i32 s11, 64, s10
	s_min_i32 s11, s11, 8
	s_abs_i32 s14, s11
	v_cvt_f32_u32_e32 v165, s14
	s_sub_i32 s22, 0, s14
	s_and_b32 s9, s9, -16
	s_sub_i32 s9, s8, s9
	v_rcp_iflag_f32_e32 v165, v165
	s_abs_i32 s8, s9
	s_xor_b32 s15, s9, s11
	s_ashr_i32 s15, s15, 31
	v_mul_f32_e32 v165, 0x4f7ffffe, v165
	v_cvt_u32_f32_e32 v165, v165
	s_nop 0
	v_readfirstlane_b32 s23, v165
	s_mul_i32 s22, s22, s23
	s_mul_hi_u32 s22, s23, s22
	s_add_i32 s23, s23, s22
	s_mul_hi_u32 s22, s8, s23
	s_mul_i32 s23, s22, s14
	s_sub_i32 s8, s8, s23
	s_add_i32 s40, s22, 1
	s_sub_i32 s23, s8, s14
	s_cmp_ge_u32 s8, s14
	s_cselect_b32 s22, s40, s22
	s_cselect_b32 s8, s23, s8
	s_add_i32 s23, s22, 1
	s_cmp_ge_u32 s8, s14
	s_cselect_b32 s8, s23, s22
	s_xor_b32 s8, s8, s15
	s_sub_i32 s8, s8, s15
	s_mul_i32 s11, s8, s11
	s_sub_i32 s9, s9, s11
	s_add_i32 s10, s10, s9
.LBB0_5226:
	s_ashr_i32 s11, s10, 31
	v_cmp_lt_i64_e32 vcc, s[12:13], v[144:145]
	s_lshl_b64 s[12:13], s[10:11], 20
	s_add_u32 s12, s72, s12
	s_addc_u32 s13, s73, s13
	s_and_b64 s[14:15], vcc, exec
	s_cselect_b32 s11, s13, s19
	s_cselect_b32 s40, s12, s18
	s_ashr_i32 s9, s8, 31
	s_lshl_b64 s[14:15], s[8:9], 20
	s_add_u32 s14, s84, s14
	s_addc_u32 s15, s85, s15
	s_and_b64 s[22:23], vcc, exec
	s_cselect_b32 s9, s15, s21
	s_cselect_b32 s41, s14, s20
	s_add_u32 s18, s18, 0x80080
	s_addc_u32 s19, s19, 0
	s_add_u32 s42, s20, 0x100
	s_addc_u32 s43, s21, 0
	s_mov_b32 s44, -2
	s_waitcnt lgkmcnt(0)
	s_waitcnt vmcnt(0)

;     __device__ __forceinline__ bool next(int i, Unit& u) const {
;         const int nwg = nM * nN; const long L = (long)i * G + c; if (L >= nwg) return false;
;         int wgid = (int)L; { const int q = nwg / NXCD, r = nwg % NXCD, xcd = wgid % NXCD, off = wgid / NXCD; wgid = (xcd < r ? xcd * (q + 1) : r * (q + 1) + (xcd - r) * q) + off; }
;         const int nig = WGM * nN, gid = wgid / nig, fm = gid * WGM, gsz = (nM - fm) < WGM ? (nM - fm) : WGM;
;         u.pm = fm + ((wgid % nig) % gsz); u.pn = (wgid % nig) / gsz; return true;
; template <class PT, class Epi>
; __device__ __forceinline__ void gemm_phase_once(LAS unsigned char* lds, const PT& S, const Epi& E, bool epi_on) {
;     ...
; #pragma unroll
;         for (int a = 0; a < 2; ++a)
; #pragma unroll
;             for (int b = 0; b < 2; ++b)
; #pragma unroll
;                 for (int m = 0; m < 4; ++m)
; #pragma unroll
;                     for (int n = 0; n < 2; ++n) acc[a][b][m][n] = (f32x4){0.f, 0.f, 0.f, 0.f};
.LBB0_5449:
	s_add_i32 s40, s40, 1
	s_mul_i32 s0, s40, s43
	s_mul_hi_u32 s1, s40, s33
	v_mov_b32_e32 v2, 0
	v_mov_b32_e32 v3, 0
	v_mov_b32_e32 v4, 0
	v_mov_b32_e32 v5, 0
	s_nop 1
	v_mfma_f32_16x16x32_bf16 v[6:9], v[2:5], v[2:5], 0
	v_mfma_f32_16x16x32_bf16 v[10:13], v[2:5], v[2:5], 0
	v_mfma_f32_16x16x32_bf16 v[14:17], v[2:5], v[2:5], 0
	v_mfma_f32_32x32x16_bf16 v[18:33], v[2:5], v[2:5], 0
	v_mfma_f32_32x32x16_bf16 v[34:49], v[2:5], v[2:5], 0
	v_mfma_f32_32x32x16_bf16 v[50:65], v[2:5], v[2:5], 0
	v_mfma_f32_32x32x16_bf16 v[66:81], v[2:5], v[2:5], 0
	v_mfma_f32_32x32x16_bf16 v[82:97], v[2:5], v[2:5], 0
	v_mfma_f32_32x32x16_bf16 v[98:113], v[2:5], v[2:5], 0
	v_mfma_f32_32x32x16_bf16 v[114:129], v[2:5], v[2:5], 0
	s_add_i32 s1, s1, s0
	s_mul_i32 s0, s40, s33
	v_readlane_b32 s17, v254, 9
	s_add_u32 s20, s0, s17
	s_addc_u32 s21, s1, s35
	v_cmp_gt_i64_e64 s[0:1], s[20:21], v[144:145]
	s_and_b64 vcc, exec, s[0:1]
	s_cbranch_vccnz .LBB0_5455
	s_ashr_i32 s16, s20, 31
	s_lshr_b32 s16, s16, 29
	s_add_i32 s18, s20, s16
	s_and_b32 s16, s18, -8
	s_sub_i32 s19, s20, s16
	s_cmp_gt_i32 s19, -1
	s_mov_b64 s[16:17], -1
	s_cbranch_scc0 .LBB0_5452
	s_lshl_b32 s22, s19, 6
	s_mov_b64 s[16:17], 0

;     __device__ __forceinline__ const char* pa(const Unit& u) const { return (const char*)(A + (size_t)u.pm * a_tile_stride + (size_t)u.pn * 512); }
;     __device__ __forceinline__ bool next(int i, Unit& u) const {
;     ...
;         const int nig = WGM * nN, gid = wgid / nig, fm = gid * WGM, gsz = (nM - fm) < WGM ? (nM - fm) : WGM;
;         u.pm = fm + ((wgid % nig) % gsz); u.pn = (wgid % nig) / gsz; return true;
;     }
;     __device__ __forceinline__ const char* pa(const Unit& u) const { return (const char*)(A + (size_t)u.pm * a_tile_stride + (size_t)((u.pn >> a_group_shift) * a_group_cols)); }
;     __device__ __forceinline__ const char* pb(const Unit& u) const { return (const char*)(Bt + (size_t)u.pn * b_tile_stride); }
; template <class PT, class Epi>
; __device__ __forceinline__ void gemm_phase_once(LAS unsigned char* lds, const PT& S, const Epi& E, bool epi_on) {
;     ...
;         const bool has_next = S.next(ui + 1, nxt);
;         const char* nA = has_next ? S.pa(nxt) : cA; const char* nB = has_next ? S.pb(nxt) : cB;
;         for (int t = 0; t < nt; t += 2) {
;             const bool last = (t == nt - 2);
;             const char* a1 = cA + (size_t)(t + 1) * kstep;
;             const char* a2 = last ? nA : cA + (size_t)(t + 2) * kstep; const char* b2 = last ? nB : cB + (size_t)(t + 2) * kstep;
;             const char* a3 = a2 + kstep; const char* b3 = b2 + kstep;
.LBB0_5454:
	s_ashr_i32 s16, s18, 3
	s_add_i32 s16, s22, s16
	s_ashr_i32 s17, s16, 31
	s_lshr_b32 s17, s17, 26
	s_add_i32 s17, s16, s17
	s_ashr_i32 s18, s17, 6
	s_lshl_b32 s18, s18, 3
	s_sub_i32 s19, 64, s18
	s_min_i32 s19, s19, 8
	s_abs_i32 s22, s19
	v_cvt_f32_u32_e32 v156, s22
	s_sub_i32 s30, 0, s22
	s_andn2_b32 s17, s17, 63
	s_sub_i32 s17, s16, s17
	v_rcp_iflag_f32_e32 v156, v156
	s_abs_i32 s16, s17
	s_xor_b32 s23, s17, s19
	s_ashr_i32 s23, s23, 31
	v_mul_f32_e32 v156, 0x4f7ffffe, v156
	v_cvt_u32_f32_e32 v156, v156
	s_nop 0
	v_readfirstlane_b32 s31, v156
	s_mul_i32 s30, s30, s31
	s_mul_hi_u32 s30, s31, s30
	s_add_i32 s31, s31, s30
	s_mul_hi_u32 s30, s16, s31
	s_mul_i32 s31, s30, s22
	s_sub_i32 s16, s16, s31
	s_add_i32 s51, s30, 1
	s_sub_i32 s31, s16, s22
	s_cmp_ge_u32 s16, s22
	s_cselect_b32 s30, s51, s30
	s_cselect_b32 s16, s31, s16
	s_add_i32 s31, s30, 1
	s_cmp_ge_u32 s16, s22
	s_cselect_b32 s16, s31, s30
	s_xor_b32 s16, s16, s23
	s_sub_i32 s16, s16, s23
	s_mul_i32 s19, s16, s19
	s_sub_i32 s17, s17, s19
	s_add_i32 s18, s18, s17
.LBB0_5455:
	s_ashr_i32 s19, s18, 31
	v_cmp_lt_i64_e32 vcc, s[20:21], v[142:143]
	s_lshl_b64 s[20:21], s[18:19], 18
	v_readlane_b32 s22, v254, 48
	v_readlane_b32 s23, v254, 49
	s_add_u32 s20, s22, s20
	s_addc_u32 s21, s23, s21
	s_and_b64 s[22:23], vcc, exec
	s_cselect_b32 s19, s21, s27
	s_cselect_b32 s51, s20, s26
	s_ashr_i32 s17, s16, 31
	s_lshl_b64 s[22:23], s[16:17], 18
	v_readlane_b32 s30, v254, 7
	v_readlane_b32 s31, v254, 8
	s_add_u32 s22, s30, s22
	s_addc_u32 s23, s31, s23
	s_and_b64 s[30:31], vcc, exec
	s_cselect_b32 s17, s23, s29
	s_cselect_b32 s52, s22, s28
	s_add_u32 s26, s26, 0x20080
	s_addc_u32 s27, s27, 0
	s_add_u32 s53, s28, 0x100
	s_addc_u32 s54, s29, 0
	s_mov_b32 s55, -2
	s_waitcnt lgkmcnt(0)

;     __device__ __forceinline__ const char* pa(const Unit& u) const { return (const char*)(A + (size_t)u.pm * a_tile_stride + (size_t)u.pn * 512); }
;     __device__ __forceinline__ bool next(int i, Unit& u) const {
;         const int nwg = nM * nN; const long L = (long)i * G + c; if (L >= nwg) return false;
;         int wgid = (int)L; { const int q = nwg / NXCD, r = nwg % NXCD, xcd = wgid % NXCD, off = wgid / NXCD; wgid = (xcd < r ? xcd * (q + 1) : r * (q + 1) + (xcd - r) * q) + off; }
;         const int nig = WGM * nN, gid = wgid / nig, fm = gid * WGM, gsz = (nM - fm) < WGM ? (nM - fm) : WGM;
;         u.pm = fm + ((wgid % nig) % gsz); u.pn = (wgid % nig) / gsz; return true;
;     }
;     __device__ __forceinline__ const char* pa(const Unit& u) const { return (const char*)(A + (size_t)u.pm * a_tile_stride + (size_t)((u.pn >> a_group_shift) * a_group_cols)); }
;     __device__ __forceinline__ const char* pb(const Unit& u) const { return (const char*)(Bt + (size_t)u.pn * b_tile_stride); }
; template <class PT, class Epi>
; __device__ __forceinline__ void gemm_phase_once(LAS unsigned char* lds, const PT& S, const Epi& E, bool epi_on) {
;     ...
; #pragma unroll
;         for (int a = 0; a < 2; ++a)
; #pragma unroll
;             for (int b = 0; b < 2; ++b)
; #pragma unroll
;                 for (int m = 0; m < 4; ++m)
; #pragma unroll
;                     for (int n = 0; n < 2; ++n) acc[a][b][m][n] = (f32x4){0.f, 0.f, 0.f, 0.f};
.LBB0_5580:
	s_add_i32 s53, s53, 1
	s_mul_i32 s0, s53, s56
	s_mul_hi_u32 s1, s53, s33
	v_mov_b32_e32 v2, 0
	v_mov_b32_e32 v3, 0
	v_mov_b32_e32 v4, 0
	v_mov_b32_e32 v5, 0
	s_nop 1
	v_mfma_f32_16x16x32_bf16 v[6:9], v[2:5], v[2:5], 0
	v_mfma_f32_16x16x32_bf16 v[10:13], v[2:5], v[2:5], 0
	v_mfma_f32_16x16x32_bf16 v[14:17], v[2:5], v[2:5], 0
	v_mfma_f32_32x32x16_bf16 v[18:33], v[2:5], v[2:5], 0
	v_mfma_f32_32x32x16_bf16 v[34:49], v[2:5], v[2:5], 0
	v_mfma_f32_16x16x32_bf16 v[50:53], v[2:5], v[2:5], 0
	v_mfma_f32_16x16x32_bf16 v[54:57], v[2:5], v[2:5], 0
	v_mfma_f32_16x16x32_bf16 v[62:65], v[2:5], v[2:5], 0
	v_mfma_f32_16x16x32_bf16 v[66:69], v[2:5], v[2:5], 0
	v_mfma_f32_32x32x16_bf16 v[74:89], v[2:5], v[2:5], 0
	v_mfma_f32_32x32x16_bf16 v[90:105], v[2:5], v[2:5], 0
	v_mfma_f32_32x32x16_bf16 v[106:121], v[2:5], v[2:5], 0
	v_mfma_f32_32x32x16_bf16 v[122:137], v[2:5], v[2:5], 0
	s_add_i32 s1, s1, s0
	s_mul_i32 s0, s53, s33
	v_readlane_b32 s25, v254, 9
	s_add_u32 s28, s0, s25
	s_addc_u32 s29, s1, s47
	v_cmp_gt_i64_e64 s[0:1], s[28:29], v[154:155]
	s_and_b64 vcc, exec, s[0:1]
	s_cbranch_vccnz .LBB0_5582
	s_ashr_i32 s24, s28, 31
	s_lshr_b32 s24, s24, 29
	s_add_i32 s24, s28, s24
	s_ashr_i32 s25, s24, 3
	s_and_b32 s24, s24, -8
	s_sub_i32 s24, s28, s24
	s_cmp_lt_i32 s24, 0
	s_cselect_b32 s26, s48, 0x160
	s_mul_i32 s24, s26, s24
	s_add_i32 s24, s24, s25
	s_mul_hi_i32 s25, s24, 0x2e8ba2e9
	s_lshr_b32 s26, s25, 31
	s_ashr_i32 s25, s25, 6
	s_add_i32 s25, s25, s26
	s_lshl_b32 s26, s25, 3
	s_sub_i32 s27, 64, s26
	s_min_i32 s27, s27, 8
	s_abs_i32 s30, s27
	v_cvt_f32_u32_e32 v70, s30
	s_sub_i32 s35, 0, s30
	s_mulk_i32 s25, 0x160
	s_sub_i32 s25, s24, s25
	v_rcp_iflag_f32_e32 v70, v70
	s_abs_i32 s24, s25
	s_xor_b32 s31, s25, s27
	s_ashr_i32 s31, s31, 31
	v_mul_f32_e32 v70, 0x4f7ffffe, v70
	v_cvt_u32_f32_e32 v70, v70
	s_nop 0
	v_readfirstlane_b32 s40, v70
	s_mul_i32 s35, s35, s40
	s_mul_hi_u32 s35, s40, s35
	s_add_i32 s40, s40, s35
	s_mul_hi_u32 s35, s24, s40
	s_mul_i32 s40, s35, s30
	s_sub_i32 s24, s24, s40
	s_add_i32 s41, s35, 1
	s_sub_i32 s40, s24, s30
	s_cmp_ge_u32 s24, s30
	s_cselect_b32 s35, s41, s35
	s_cselect_b32 s24, s40, s24
	s_add_i32 s40, s35, 1
	s_cmp_ge_u32 s24, s30
	s_cselect_b32 s24, s40, s35
	s_xor_b32 s24, s24, s31
	s_sub_i32 s24, s24, s31
	s_mul_i32 s27, s24, s27
	s_sub_i32 s25, s25, s27
	s_add_i32 s26, s25, s26
.LBB0_5582:
	s_ashr_i32 s27, s26, 31
	v_cmp_lt_i64_e32 vcc, s[28:29], v[152:153]
	s_lshl_b64 s[28:29], s[26:27], 20
	s_add_u32 s28, s72, s28
	s_addc_u32 s29, s73, s29
	s_and_b64 s[30:31], vcc, exec
	s_cselect_b32 s27, s29, s37
	s_cselect_b32 s35, s28, s36
	s_ashr_i32 s25, s24, 31
	s_lshl_b64 s[30:31], s[24:25], 20
	s_add_u32 s30, s76, s30
	s_addc_u32 s31, s77, s31
	s_and_b64 s[40:41], vcc, exec
	s_cselect_b32 s25, s31, s39
	s_cselect_b32 s62, s30, s38
	s_add_u32 s63, s38, 0x100
	s_addc_u32 s64, s39, 0
	s_mov_b32 s65, -2
	s_waitcnt vmcnt(0)
	s_waitcnt lgkmcnt(0)

;     __device__ __forceinline__ bool next(int i, Unit& u) const {
;         const int nwg = nM * nN; const long L = (long)i * G + c; if (L >= nwg) return false;
;         int wgid = (int)L; { const int q = nwg / NXCD, r = nwg % NXCD, xcd = wgid % NXCD, off = wgid / NXCD; wgid = (xcd < r ? xcd * (q + 1) : r * (q + 1) + (xcd - r) * q) + off; }
;         const int nig = WGM * nN, gid = wgid / nig, fm = gid * WGM, gsz = (nM - fm) < WGM ? (nM - fm) : WGM;
;         u.pm = fm + ((wgid % nig) % gsz); u.pn = (wgid % nig) / gsz; return true;
; template <class PT, class Epi>
; __device__ __forceinline__ void gemm_phase_once(LAS unsigned char* lds, const PT& S, const Epi& E, bool epi_on) {
;     ...
; #pragma unroll
;         for (int a = 0; a < 2; ++a)
; #pragma unroll
;             for (int b = 0; b < 2; ++b)
; #pragma unroll
;                 for (int m = 0; m < 4; ++m)
; #pragma unroll
;                     for (int n = 0; n < 2; ++n) acc[a][b][m][n] = (f32x4){0.f, 0.f, 0.f, 0.f};
.LBB0_5731:
	s_add_i32 s31, s31, 1
	s_mul_i32 s0, s31, s36
	s_mul_hi_u32 s1, s31, s33
	v_mov_b32_e32 v0, 0
	v_mov_b32_e32 v1, 0
	v_mov_b32_e32 v2, 0
	v_mov_b32_e32 v3, 0
	s_nop 1
	v_mfma_f32_16x16x32_bf16 v[4:7], v[0:3], v[0:3], 0
	v_mfma_f32_16x16x32_bf16 v[8:11], v[0:3], v[0:3], 0
	v_mfma_f32_16x16x32_bf16 v[12:15], v[0:3], v[0:3], 0
	v_mfma_f32_32x32x16_bf16 v[16:31], v[0:3], v[0:3], 0
	v_mfma_f32_32x32x16_bf16 v[32:47], v[0:3], v[0:3], 0
	v_mfma_f32_32x32x16_bf16 v[48:63], v[0:3], v[0:3], 0
	v_mfma_f32_32x32x16_bf16 v[64:79], v[0:3], v[0:3], 0
	v_mfma_f32_32x32x16_bf16 v[80:95], v[0:3], v[0:3], 0
	v_mfma_f32_32x32x16_bf16 v[96:111], v[0:3], v[0:3], 0
	v_mfma_f32_32x32x16_bf16 v[112:127], v[0:3], v[0:3], 0
	s_add_i32 s1, s1, s0
	s_mul_i32 s0, s31, s33
	v_readlane_b32 s2, v254, 9
	s_add_u32 s6, s0, s2
	s_addc_u32 s7, s1, s25
	v_cmp_gt_i64_e64 s[0:1], s[6:7], v[142:143]
	v_cmp_lt_i64_e64 s[2:3], s[6:7], v[140:141]
	s_and_b64 vcc, exec, s[0:1]
	s_cbranch_vccnz .LBB0_5737
	s_ashr_i32 s7, s6, 31
	s_lshr_b32 s7, s7, 29
	s_add_i32 s22, s6, s7
	s_and_b32 s7, s22, -8
	s_sub_i32 s23, s6, s7
	s_cmp_gt_i32 s23, -1
	s_mov_b64 s[6:7], -1
	s_cbranch_scc0 .LBB0_5734
	s_lshl_b32 s43, s23, 6
	s_mov_b64 s[6:7], 0

;     __device__ __forceinline__ const char* pa(const Unit& u) const { return (const char*)(A + (size_t)u.pm * a_tile_stride + (size_t)u.pn * 512); }
;     __device__ __forceinline__ bool next(int i, Unit& u) const {
;     ...
;         const int nig = WGM * nN, gid = wgid / nig, fm = gid * WGM, gsz = (nM - fm) < WGM ? (nM - fm) : WGM;
;         u.pm = fm + ((wgid % nig) % gsz); u.pn = (wgid % nig) / gsz; return true;
;     }
;     __device__ __forceinline__ const char* pa(const Unit& u) const { return (const char*)(A + (size_t)u.pm * a_tile_stride + (size_t)((u.pn >> a_group_shift) * a_group_cols)); }
;     __device__ __forceinline__ const char* pb(const Unit& u) const { return (const char*)(Bt + (size_t)u.pn * b_tile_stride); }
; template <class PT, class Epi>
; __device__ __forceinline__ void gemm_phase_once(LAS unsigned char* lds, const PT& S, const Epi& E, bool epi_on) {
;     ...
;         const bool has_next = S.next(ui + 1, nxt);
;         const char* nA = has_next ? S.pa(nxt) : cA; const char* nB = has_next ? S.pb(nxt) : cB;
.LBB0_5736:
	s_ashr_i32 s6, s22, 3
	s_add_i32 s6, s43, s6
	s_ashr_i32 s7, s6, 31
	s_lshr_b32 s7, s7, 26
	s_add_i32 s7, s6, s7
	s_ashr_i32 s22, s7, 6
	s_lshl_b32 s22, s22, 3
	s_sub_i32 s23, 64, s22
	s_min_i32 s23, s23, 8
	s_abs_i32 s43, s23
	v_cvt_f32_u32_e32 v154, s43
	s_sub_i32 s47, 0, s43
	s_andn2_b32 s7, s7, 63
	s_sub_i32 s6, s6, s7
	v_rcp_iflag_f32_e32 v154, v154
	s_abs_i32 s7, s6
	s_xor_b32 s44, s6, s23
	s_ashr_i32 s44, s44, 31
	v_mul_f32_e32 v154, 0x4f7ffffe, v154
	v_cvt_u32_f32_e32 v154, v154
	s_nop 0
	v_readfirstlane_b32 s48, v154
	s_mul_i32 s47, s47, s48
	s_mul_hi_u32 s47, s48, s47
	s_add_i32 s48, s48, s47
	s_mul_hi_u32 s47, s7, s48
	s_mul_i32 s48, s47, s43
	s_sub_i32 s7, s7, s48
	s_add_i32 s49, s47, 1
	s_sub_i32 s48, s7, s43
	s_cmp_ge_u32 s7, s43
	s_cselect_b32 s47, s49, s47
	s_cselect_b32 s7, s48, s7
	s_add_i32 s48, s47, 1
	s_cmp_ge_u32 s7, s43
	s_cselect_b32 s7, s48, s47
	s_xor_b32 s7, s7, s44
	s_sub_i32 s43, s7, s44
	s_mul_i32 s7, s43, s23
	s_sub_i32 s6, s6, s7
	s_add_i32 s44, s22, s6
.LBB0_5737:
	v_cndmask_b32_e64 v154, 0, 1, s[2:3]
	v_cmp_ne_u32_e64 s[6:7], 1, v154
	s_andn2_b64 vcc, exec, s[2:3]
	s_mov_b64 s[2:3], s[18:19]
	s_cbranch_vccnz .LBB0_5739
	s_mul_i32 s2, s44, 0x2c0000
	s_mul_hi_i32 s3, s44, 0x2c0000
	s_add_u32 s2, s78, s2
	s_addc_u32 s3, s79, s3

; #define PG8_STAGE(bufoff, gbase, voff) do { _Pragma("unroll") for (int _i = 0; _i < 2; ++_i) \
;         __builtin_amdgcn_global_load_lds((const unsigned*)((const char*)(gbase) + (voff)[_i]), (LAS unsigned*)(lds + (bufoff) + ldsw + _i * 8192), 16, 0, 0); } while (0)
; #define PG8_LDA(dst, b, h) do { _Pragma("unroll") for (int m = 0; m < 4; ++m) _Pragma("unroll") for (int k = 0; k < 2; ++k) dst[m][k] = *(const LAS bf16x8*)(lds + PG8_SA(b, h) + aoff + m * 2048 + k * 1024); } while (0)
; #define PG8_LDB(dst, b, h) do { _Pragma("unroll") for (int n = 0; n < 2; ++n) _Pragma("unroll") for (int k = 0; k < 2; ++k) dst[n][k] = *(const LAS bf16x8*)(lds + PG8_SB(b, h) + boff + n * 2048 + k * 1024); } while (0)
; #define PG8_SCHED __builtin_amdgcn_sched_barrier(0)
; template <class PT, class Epi>
; __device__ __forceinline__ void gemm_phase_once(LAS unsigned char* lds, const PT& S, const Epi& E, bool epi_on) {
;     ...
;             const char* a1 = cA + (size_t)(t + 1) * kstep;
;             const char* a2 = last ? nA : cA + (size_t)(t + 2) * kstep; const char* b2 = last ? nB : cB + (size_t)(t + 2) * kstep;
;             const char* a3 = a2 + kstep; const char* b3 = b2 + kstep;
;             PG8_LDB(B0, 0, 0); PG8_SCHED; PG8_LDA(At, 0, 0); PG8_STAGE(PG8_SA(1, 1), a1 + hstepA, voffA);
.LBB0_5741:
	s_add_u32 s18, s18, 0x160080
	s_addc_u32 s19, s19, 0
	s_add_u32 s47, s20, 0x100
	s_addc_u32 s48, s21, 0
	s_mov_b32 s49, -2
	s_waitcnt lgkmcnt(0)
